# merge K=512 projection GEMM also on the LDS-DMA mainloop (three fragment slots, group-wise LDS->register streaming)
# speedup vs baseline: 1.0794x; 1.0097x over previous
.Lgp_ma:
	s_add_u32 m0, s14, 0x800
	s_nop 0
	global_load_lds_dwordx4 v[148:149], off
	s_add_u32 m0, s14, 0x1800
	s_nop 0
	global_load_lds_dwordx4 v[152:153], off
	s_add_u32 m0, s14, 0x2800
	s_nop 0
	global_load_lds_dwordx4 v[156:157], off
	s_add_u32 m0, s14, 0x3800
	s_nop 0
	global_load_lds_dwordx4 v[160:161], off
	s_add_u32 m0, s14, 0x4800
	s_nop 0
	global_load_lds_dwordx4 v[150:151], off
	s_add_u32 m0, s14, 0x5800
	s_nop 0
	global_load_lds_dwordx4 v[154:155], off
	s_add_u32 m0, s14, 0x6800
	s_nop 0
	global_load_lds_dwordx4 v[158:159], off
	s_add_u32 m0, s14, 0x7800
	s_nop 0
	global_load_lds_dwordx4 v[162:163], off
	s_add_u32 m0, s14, 0x8780
	s_nop 0
	global_load_lds_dwordx4 v[148:149], off offset:128
	s_add_u32 m0, s14, 0x9780
	s_nop 0
	global_load_lds_dwordx4 v[152:153], off offset:128
	s_add_u32 m0, s14, 0xa780
	s_nop 0
	global_load_lds_dwordx4 v[156:157], off offset:128
	s_add_u32 m0, s14, 0xb780
	s_nop 0
	global_load_lds_dwordx4 v[160:161], off offset:128
	s_add_u32 m0, s14, 0xc780
	s_nop 0
	global_load_lds_dwordx4 v[150:151], off offset:128
	s_add_u32 m0, s14, 0xd780
	s_nop 0
	global_load_lds_dwordx4 v[154:155], off offset:128
	s_add_u32 m0, s14, 0xe780
	s_nop 0
	global_load_lds_dwordx4 v[158:159], off offset:128
	s_add_u32 m0, s14, 0xf780
	s_nop 0
	global_load_lds_dwordx4 v[162:163], off offset:128
	s_waitcnt vmcnt(8)
	s_barrier
	ds_read_b128 v[66:69], v130 offset:2048
	ds_read_b128 v[70:73], v130 offset:6144
	ds_read_b128 v[74:77], v134 offset:2048
	ds_read_b128 v[78:81], v134 offset:6144
	ds_read_b128 v[82:85], v131 offset:2048
	ds_read_b128 v[86:89], v131 offset:6144
	ds_read_b128 v[90:93], v135 offset:2048
	ds_read_b128 v[94:97], v135 offset:6144
	ds_read_b128 v[98:101], v132 offset:2048
	ds_read_b128 v[102:105], v132 offset:6144
	ds_read_b128 v[106:109], v136 offset:2048
	ds_read_b128 v[110:113], v136 offset:6144
	ds_read_b128 v[114:117], v133 offset:2048
	ds_read_b128 v[118:121], v133 offset:6144
	ds_read_b128 v[122:125], v137 offset:2048
	ds_read_b128 v[126:129], v137 offset:6144
	s_waitcnt lgkmcnt(0)
	s_barrier
	s_add_u32 m0, s14, 0x700
	s_nop 0
	global_load_lds_dwordx4 v[148:149], off offset:256
	s_add_u32 m0, s14, 0x1700
	s_nop 0
	global_load_lds_dwordx4 v[152:153], off offset:256
	s_add_u32 m0, s14, 0x2700
	s_nop 0
	global_load_lds_dwordx4 v[156:157], off offset:256
	s_add_u32 m0, s14, 0x3700
	s_nop 0
	global_load_lds_dwordx4 v[160:161], off offset:256
	s_add_u32 m0, s14, 0x4700
	s_nop 0
	global_load_lds_dwordx4 v[150:151], off offset:256
	s_add_u32 m0, s14, 0x5700
	s_nop 0
	global_load_lds_dwordx4 v[154:155], off offset:256
	s_add_u32 m0, s14, 0x6700
	s_nop 0
	global_load_lds_dwordx4 v[158:159], off offset:256
	s_add_u32 m0, s14, 0x7700
	s_nop 0
	global_load_lds_dwordx4 v[162:163], off offset:256
	v_mfma_f32_32x32x16_bf16 v[50:65], v[66:69], v[74:77], 0
	v_mfma_f32_32x32x16_bf16 v[34:49], v[66:69], v[78:81], 0
	v_mfma_f32_32x32x16_bf16 v[18:33], v[70:73], v[74:77], 0
	v_mfma_f32_32x32x16_bf16 v[2:17], v[70:73], v[78:81], 0
	s_waitcnt vmcnt(8)
	s_barrier
	ds_read_b128 v[66:69], v130 offset:34816
	ds_read_b128 v[70:73], v130 offset:38912
	ds_read_b128 v[74:77], v134 offset:34816
	ds_read_b128 v[78:81], v134 offset:38912
	v_mfma_f32_32x32x16_bf16 v[50:65], v[82:85], v[90:93], v[50:65]
	v_mfma_f32_32x32x16_bf16 v[34:49], v[82:85], v[94:97], v[34:49]
	v_mfma_f32_32x32x16_bf16 v[18:33], v[86:89], v[90:93], v[18:33]
	v_mfma_f32_32x32x16_bf16 v[2:17], v[86:89], v[94:97], v[2:17]
	ds_read_b128 v[82:85], v131 offset:34816
	ds_read_b128 v[86:89], v131 offset:38912
	ds_read_b128 v[90:93], v135 offset:34816
	ds_read_b128 v[94:97], v135 offset:38912
	v_mfma_f32_32x32x16_bf16 v[50:65], v[98:101], v[106:109], v[50:65]
	v_mfma_f32_32x32x16_bf16 v[34:49], v[98:101], v[110:113], v[34:49]
	v_mfma_f32_32x32x16_bf16 v[18:33], v[102:105], v[106:109], v[18:33]
	v_mfma_f32_32x32x16_bf16 v[2:17], v[102:105], v[110:113], v[2:17]
	ds_read_b128 v[98:101], v132 offset:34816
	ds_read_b128 v[102:105], v132 offset:38912
	ds_read_b128 v[106:109], v136 offset:34816
	ds_read_b128 v[110:113], v136 offset:38912
	v_mfma_f32_32x32x16_bf16 v[50:65], v[114:117], v[122:125], v[50:65]
	v_mfma_f32_32x32x16_bf16 v[34:49], v[114:117], v[126:129], v[34:49]
	v_mfma_f32_32x32x16_bf16 v[18:33], v[118:121], v[122:125], v[18:33]
	v_mfma_f32_32x32x16_bf16 v[2:17], v[118:121], v[126:129], v[2:17]
	ds_read_b128 v[114:117], v133 offset:34816
	ds_read_b128 v[118:121], v133 offset:38912
	ds_read_b128 v[122:125], v137 offset:34816
	ds_read_b128 v[126:129], v137 offset:38912
	s_waitcnt lgkmcnt(0)
	s_barrier
	v_mfma_f32_32x32x16_bf16 v[50:65], v[66:69], v[74:77], v[50:65]
	s_add_u32 m0, s14, 0x8680
	s_nop 0
	global_load_lds_dwordx4 v[148:149], off offset:384
	s_add_u32 m0, s14, 0x9680
	s_nop 0
	global_load_lds_dwordx4 v[152:153], off offset:384
	v_mfma_f32_32x32x16_bf16 v[34:49], v[66:69], v[78:81], v[34:49]
	s_add_u32 m0, s14, 0xa680
	s_nop 0
	global_load_lds_dwordx4 v[156:157], off offset:384
	s_add_u32 m0, s14, 0xb680
	s_nop 0
	global_load_lds_dwordx4 v[160:161], off offset:384
	v_mfma_f32_32x32x16_bf16 v[18:33], v[70:73], v[74:77], v[18:33]
	s_add_u32 m0, s14, 0xc680
	s_nop 0
	global_load_lds_dwordx4 v[150:151], off offset:384
	s_add_u32 m0, s14, 0xd680
	s_nop 0
	global_load_lds_dwordx4 v[154:155], off offset:384
	v_mfma_f32_32x32x16_bf16 v[2:17], v[70:73], v[78:81], v[2:17]
	s_add_u32 m0, s14, 0xe680
	s_nop 0
	global_load_lds_dwordx4 v[158:159], off offset:384
	s_add_u32 m0, s14, 0xf680
	s_nop 0
	global_load_lds_dwordx4 v[162:163], off offset:384
	s_waitcnt vmcnt(8)
	s_barrier
	ds_read_b128 v[66:69], v130 offset:2048
	ds_read_b128 v[70:73], v130 offset:6144
	ds_read_b128 v[74:77], v134 offset:2048
	ds_read_b128 v[78:81], v134 offset:6144
	v_mfma_f32_32x32x16_bf16 v[50:65], v[82:85], v[90:93], v[50:65]
	v_mfma_f32_32x32x16_bf16 v[34:49], v[82:85], v[94:97], v[34:49]
	v_mfma_f32_32x32x16_bf16 v[18:33], v[86:89], v[90:93], v[18:33]
	v_mfma_f32_32x32x16_bf16 v[2:17], v[86:89], v[94:97], v[2:17]
	ds_read_b128 v[82:85], v131 offset:2048
	ds_read_b128 v[86:89], v131 offset:6144
	ds_read_b128 v[90:93], v135 offset:2048
	ds_read_b128 v[94:97], v135 offset:6144
	v_mfma_f32_32x32x16_bf16 v[50:65], v[98:101], v[106:109], v[50:65]
	v_mfma_f32_32x32x16_bf16 v[34:49], v[98:101], v[110:113], v[34:49]
	v_mfma_f32_32x32x16_bf16 v[18:33], v[102:105], v[106:109], v[18:33]
	v_mfma_f32_32x32x16_bf16 v[2:17], v[102:105], v[110:113], v[2:17]
	ds_read_b128 v[98:101], v132 offset:2048
	ds_read_b128 v[102:105], v132 offset:6144
	ds_read_b128 v[106:109], v136 offset:2048
	ds_read_b128 v[110:113], v136 offset:6144
	v_mfma_f32_32x32x16_bf16 v[50:65], v[114:117], v[122:125], v[50:65]
	v_mfma_f32_32x32x16_bf16 v[34:49], v[114:117], v[126:129], v[34:49]
	v_mfma_f32_32x32x16_bf16 v[18:33], v[118:121], v[122:125], v[18:33]
	v_mfma_f32_32x32x16_bf16 v[2:17], v[118:121], v[126:129], v[2:17]
	ds_read_b128 v[114:117], v133 offset:2048
	ds_read_b128 v[118:121], v133 offset:6144
	ds_read_b128 v[122:125], v137 offset:2048
	ds_read_b128 v[126:129], v137 offset:6144
	s_waitcnt lgkmcnt(0)
	s_barrier
	v_mfma_f32_32x32x16_bf16 v[50:65], v[66:69], v[74:77], v[50:65]
	s_add_u32 m0, s14, 0x600
	s_nop 0
	global_load_lds_dwordx4 v[148:149], off offset:512
	s_add_u32 m0, s14, 0x1600
	s_nop 0
	global_load_lds_dwordx4 v[152:153], off offset:512
	v_mfma_f32_32x32x16_bf16 v[34:49], v[66:69], v[78:81], v[34:49]
	s_add_u32 m0, s14, 0x2600
	s_nop 0
	global_load_lds_dwordx4 v[156:157], off offset:512
	s_add_u32 m0, s14, 0x3600
	s_nop 0
	global_load_lds_dwordx4 v[160:161], off offset:512
	v_mfma_f32_32x32x16_bf16 v[18:33], v[70:73], v[74:77], v[18:33]
	s_add_u32 m0, s14, 0x4600
	s_nop 0
	global_load_lds_dwordx4 v[150:151], off offset:512
	s_add_u32 m0, s14, 0x5600
	s_nop 0
	global_load_lds_dwordx4 v[154:155], off offset:512
	v_mfma_f32_32x32x16_bf16 v[2:17], v[70:73], v[78:81], v[2:17]
	s_add_u32 m0, s14, 0x6600
	s_nop 0
	global_load_lds_dwordx4 v[158:159], off offset:512
	s_add_u32 m0, s14, 0x7600
	s_nop 0
	global_load_lds_dwordx4 v[162:163], off offset:512
	s_waitcnt vmcnt(8)
	s_barrier
	ds_read_b128 v[66:69], v130 offset:34816
	ds_read_b128 v[70:73], v130 offset:38912
	ds_read_b128 v[74:77], v134 offset:34816
	ds_read_b128 v[78:81], v134 offset:38912
	v_mfma_f32_32x32x16_bf16 v[50:65], v[82:85], v[90:93], v[50:65]
	v_mfma_f32_32x32x16_bf16 v[34:49], v[82:85], v[94:97], v[34:49]
	v_mfma_f32_32x32x16_bf16 v[18:33], v[86:89], v[90:93], v[18:33]
	v_mfma_f32_32x32x16_bf16 v[2:17], v[86:89], v[94:97], v[2:17]
	ds_read_b128 v[82:85], v131 offset:34816
	ds_read_b128 v[86:89], v131 offset:38912
	ds_read_b128 v[90:93], v135 offset:34816
	ds_read_b128 v[94:97], v135 offset:38912
	v_mfma_f32_32x32x16_bf16 v[50:65], v[98:101], v[106:109], v[50:65]
	v_mfma_f32_32x32x16_bf16 v[34:49], v[98:101], v[110:113], v[34:49]
	v_mfma_f32_32x32x16_bf16 v[18:33], v[102:105], v[106:109], v[18:33]
	v_mfma_f32_32x32x16_bf16 v[2:17], v[102:105], v[110:113], v[2:17]
	ds_read_b128 v[98:101], v132 offset:34816
	ds_read_b128 v[102:105], v132 offset:38912
	ds_read_b128 v[106:109], v136 offset:34816
	ds_read_b128 v[110:113], v136 offset:38912
	v_mfma_f32_32x32x16_bf16 v[50:65], v[114:117], v[122:125], v[50:65]
	v_mfma_f32_32x32x16_bf16 v[34:49], v[114:117], v[126:129], v[34:49]
	v_mfma_f32_32x32x16_bf16 v[18:33], v[118:121], v[122:125], v[18:33]
	v_mfma_f32_32x32x16_bf16 v[2:17], v[118:121], v[126:129], v[2:17]
	ds_read_b128 v[114:117], v133 offset:34816
	ds_read_b128 v[118:121], v133 offset:38912
	ds_read_b128 v[122:125], v137 offset:34816
	ds_read_b128 v[126:129], v137 offset:38912
	s_waitcnt lgkmcnt(0)
	s_barrier
	v_mfma_f32_32x32x16_bf16 v[50:65], v[66:69], v[74:77], v[50:65]
	s_add_u32 m0, s14, 0x8580
	s_nop 0
	global_load_lds_dwordx4 v[148:149], off offset:640
	s_add_u32 m0, s14, 0x9580
	s_nop 0
	global_load_lds_dwordx4 v[152:153], off offset:640
	v_mfma_f32_32x32x16_bf16 v[34:49], v[66:69], v[78:81], v[34:49]
	s_add_u32 m0, s14, 0xa580
	s_nop 0
	global_load_lds_dwordx4 v[156:157], off offset:640
	s_add_u32 m0, s14, 0xb580
	s_nop 0
	global_load_lds_dwordx4 v[160:161], off offset:640
	v_mfma_f32_32x32x16_bf16 v[18:33], v[70:73], v[74:77], v[18:33]
	s_add_u32 m0, s14, 0xc580
	s_nop 0
	global_load_lds_dwordx4 v[150:151], off offset:640
	s_add_u32 m0, s14, 0xd580
	s_nop 0
	global_load_lds_dwordx4 v[154:155], off offset:640
	v_mfma_f32_32x32x16_bf16 v[2:17], v[70:73], v[78:81], v[2:17]
	s_add_u32 m0, s14, 0xe580
	s_nop 0
	global_load_lds_dwordx4 v[158:159], off offset:640
	s_add_u32 m0, s14, 0xf580
	s_nop 0
	global_load_lds_dwordx4 v[162:163], off offset:640
	s_waitcnt vmcnt(8)
	s_barrier
	ds_read_b128 v[66:69], v130 offset:2048
	ds_read_b128 v[70:73], v130 offset:6144
	ds_read_b128 v[74:77], v134 offset:2048
	ds_read_b128 v[78:81], v134 offset:6144
	v_mfma_f32_32x32x16_bf16 v[50:65], v[82:85], v[90:93], v[50:65]
	v_mfma_f32_32x32x16_bf16 v[34:49], v[82:85], v[94:97], v[34:49]
	v_mfma_f32_32x32x16_bf16 v[18:33], v[86:89], v[90:93], v[18:33]
	v_mfma_f32_32x32x16_bf16 v[2:17], v[86:89], v[94:97], v[2:17]
	ds_read_b128 v[82:85], v131 offset:2048
	ds_read_b128 v[86:89], v131 offset:6144
	ds_read_b128 v[90:93], v135 offset:2048
	ds_read_b128 v[94:97], v135 offset:6144
	v_mfma_f32_32x32x16_bf16 v[50:65], v[98:101], v[106:109], v[50:65]
	v_mfma_f32_32x32x16_bf16 v[34:49], v[98:101], v[110:113], v[34:49]
	v_mfma_f32_32x32x16_bf16 v[18:33], v[102:105], v[106:109], v[18:33]
	v_mfma_f32_32x32x16_bf16 v[2:17], v[102:105], v[110:113], v[2:17]
	ds_read_b128 v[98:101], v132 offset:2048
	ds_read_b128 v[102:105], v132 offset:6144
	ds_read_b128 v[106:109], v136 offset:2048
	ds_read_b128 v[110:113], v136 offset:6144
	v_mfma_f32_32x32x16_bf16 v[50:65], v[114:117], v[122:125], v[50:65]
	v_mfma_f32_32x32x16_bf16 v[34:49], v[114:117], v[126:129], v[34:49]
	v_mfma_f32_32x32x16_bf16 v[18:33], v[118:121], v[122:125], v[18:33]
	v_mfma_f32_32x32x16_bf16 v[2:17], v[118:121], v[126:129], v[2:17]
	ds_read_b128 v[114:117], v133 offset:2048
	ds_read_b128 v[118:121], v133 offset:6144
	ds_read_b128 v[122:125], v137 offset:2048
	ds_read_b128 v[126:129], v137 offset:6144
	s_waitcnt lgkmcnt(0)
	s_barrier
	v_mfma_f32_32x32x16_bf16 v[50:65], v[66:69], v[74:77], v[50:65]
	s_add_u32 m0, s14, 0x500
	s_nop 0
	global_load_lds_dwordx4 v[148:149], off offset:768
	s_add_u32 m0, s14, 0x1500
	s_nop 0
	global_load_lds_dwordx4 v[152:153], off offset:768
	v_mfma_f32_32x32x16_bf16 v[34:49], v[66:69], v[78:81], v[34:49]
	s_add_u32 m0, s14, 0x2500
	s_nop 0
	global_load_lds_dwordx4 v[156:157], off offset:768
	s_add_u32 m0, s14, 0x3500
	s_nop 0
	global_load_lds_dwordx4 v[160:161], off offset:768
	v_mfma_f32_32x32x16_bf16 v[18:33], v[70:73], v[74:77], v[18:33]
	s_add_u32 m0, s14, 0x4500
	s_nop 0
	global_load_lds_dwordx4 v[150:151], off offset:768
	s_add_u32 m0, s14, 0x5500
	s_nop 0
	global_load_lds_dwordx4 v[154:155], off offset:768
	v_mfma_f32_32x32x16_bf16 v[2:17], v[70:73], v[78:81], v[2:17]
	s_add_u32 m0, s14, 0x6500
	s_nop 0
	global_load_lds_dwordx4 v[158:159], off offset:768
	s_add_u32 m0, s14, 0x7500
	s_nop 0
	global_load_lds_dwordx4 v[162:163], off offset:768
	s_waitcnt vmcnt(8)
	s_barrier
	ds_read_b128 v[66:69], v130 offset:34816
	ds_read_b128 v[70:73], v130 offset:38912
	ds_read_b128 v[74:77], v134 offset:34816
	ds_read_b128 v[78:81], v134 offset:38912
	v_mfma_f32_32x32x16_bf16 v[50:65], v[82:85], v[90:93], v[50:65]
	v_mfma_f32_32x32x16_bf16 v[34:49], v[82:85], v[94:97], v[34:49]
	v_mfma_f32_32x32x16_bf16 v[18:33], v[86:89], v[90:93], v[18:33]
	v_mfma_f32_32x32x16_bf16 v[2:17], v[86:89], v[94:97], v[2:17]
	ds_read_b128 v[82:85], v131 offset:34816
	ds_read_b128 v[86:89], v131 offset:38912
	ds_read_b128 v[90:93], v135 offset:34816
	ds_read_b128 v[94:97], v135 offset:38912
	v_mfma_f32_32x32x16_bf16 v[50:65], v[98:101], v[106:109], v[50:65]
	v_mfma_f32_32x32x16_bf16 v[34:49], v[98:101], v[110:113], v[34:49]
	v_mfma_f32_32x32x16_bf16 v[18:33], v[102:105], v[106:109], v[18:33]
	v_mfma_f32_32x32x16_bf16 v[2:17], v[102:105], v[110:113], v[2:17]
	ds_read_b128 v[98:101], v132 offset:34816
	ds_read_b128 v[102:105], v132 offset:38912
	ds_read_b128 v[106:109], v136 offset:34816
	ds_read_b128 v[110:113], v136 offset:38912
	v_mfma_f32_32x32x16_bf16 v[50:65], v[114:117], v[122:125], v[50:65]
	v_mfma_f32_32x32x16_bf16 v[34:49], v[114:117], v[126:129], v[34:49]
	v_mfma_f32_32x32x16_bf16 v[18:33], v[118:121], v[122:125], v[18:33]
	v_mfma_f32_32x32x16_bf16 v[2:17], v[118:121], v[126:129], v[2:17]
	ds_read_b128 v[114:117], v133 offset:34816
	ds_read_b128 v[118:121], v133 offset:38912
	ds_read_b128 v[122:125], v137 offset:34816
	ds_read_b128 v[126:129], v137 offset:38912
	s_waitcnt lgkmcnt(0)
	s_barrier
	v_mfma_f32_32x32x16_bf16 v[50:65], v[66:69], v[74:77], v[50:65]
	s_add_u32 m0, s14, 0x8480
	s_nop 0
	global_load_lds_dwordx4 v[148:149], off offset:896
	s_add_u32 m0, s14, 0x9480
	s_nop 0
	global_load_lds_dwordx4 v[152:153], off offset:896
	v_mfma_f32_32x32x16_bf16 v[34:49], v[66:69], v[78:81], v[34:49]
	s_add_u32 m0, s14, 0xa480
	s_nop 0
	global_load_lds_dwordx4 v[156:157], off offset:896
	s_add_u32 m0, s14, 0xb480
	s_nop 0
	global_load_lds_dwordx4 v[160:161], off offset:896
	v_mfma_f32_32x32x16_bf16 v[18:33], v[70:73], v[74:77], v[18:33]
	s_add_u32 m0, s14, 0xc480
	s_nop 0
	global_load_lds_dwordx4 v[150:151], off offset:896
	s_add_u32 m0, s14, 0xd480
	s_nop 0
	global_load_lds_dwordx4 v[154:155], off offset:896
	v_mfma_f32_32x32x16_bf16 v[2:17], v[70:73], v[78:81], v[2:17]
	s_add_u32 m0, s14, 0xe480
	s_nop 0
	global_load_lds_dwordx4 v[158:159], off offset:896
	s_add_u32 m0, s14, 0xf480
	s_nop 0
	global_load_lds_dwordx4 v[162:163], off offset:896
	s_waitcnt vmcnt(8)
	s_barrier
	ds_read_b128 v[66:69], v130 offset:2048
	ds_read_b128 v[70:73], v130 offset:6144
	ds_read_b128 v[74:77], v134 offset:2048
	ds_read_b128 v[78:81], v134 offset:6144
	v_mfma_f32_32x32x16_bf16 v[50:65], v[82:85], v[90:93], v[50:65]
	v_mfma_f32_32x32x16_bf16 v[34:49], v[82:85], v[94:97], v[34:49]
	v_mfma_f32_32x32x16_bf16 v[18:33], v[86:89], v[90:93], v[18:33]
	v_mfma_f32_32x32x16_bf16 v[2:17], v[86:89], v[94:97], v[2:17]
	ds_read_b128 v[82:85], v131 offset:2048
	ds_read_b128 v[86:89], v131 offset:6144
	ds_read_b128 v[90:93], v135 offset:2048
	ds_read_b128 v[94:97], v135 offset:6144
	v_mfma_f32_32x32x16_bf16 v[50:65], v[98:101], v[106:109], v[50:65]
	v_mfma_f32_32x32x16_bf16 v[34:49], v[98:101], v[110:113], v[34:49]
	v_mfma_f32_32x32x16_bf16 v[18:33], v[102:105], v[106:109], v[18:33]
	v_mfma_f32_32x32x16_bf16 v[2:17], v[102:105], v[110:113], v[2:17]
	ds_read_b128 v[98:101], v132 offset:2048
	ds_read_b128 v[102:105], v132 offset:6144
	ds_read_b128 v[106:109], v136 offset:2048
	ds_read_b128 v[110:113], v136 offset:6144
	v_mfma_f32_32x32x16_bf16 v[50:65], v[114:117], v[122:125], v[50:65]
	v_mfma_f32_32x32x16_bf16 v[34:49], v[114:117], v[126:129], v[34:49]
	v_mfma_f32_32x32x16_bf16 v[18:33], v[118:121], v[122:125], v[18:33]
	v_mfma_f32_32x32x16_bf16 v[2:17], v[118:121], v[126:129], v[2:17]
	ds_read_b128 v[114:117], v133 offset:2048
	ds_read_b128 v[118:121], v133 offset:6144
	ds_read_b128 v[122:125], v137 offset:2048
	ds_read_b128 v[126:129], v137 offset:6144
	s_waitcnt lgkmcnt(0)
	s_barrier
	v_mfma_f32_32x32x16_bf16 v[50:65], v[66:69], v[74:77], v[50:65]
	s_add_u32 m0, s14, 0x400
	s_nop 0
	global_load_lds_dwordx4 v[148:149], off offset:1024
	s_add_u32 m0, s14, 0x1400
	s_nop 0
	global_load_lds_dwordx4 v[152:153], off offset:1024
	v_mfma_f32_32x32x16_bf16 v[34:49], v[66:69], v[78:81], v[34:49]
	s_add_u32 m0, s14, 0x2400
	s_nop 0
	global_load_lds_dwordx4 v[156:157], off offset:1024
	s_add_u32 m0, s14, 0x3400
	s_nop 0
	global_load_lds_dwordx4 v[160:161], off offset:1024
	v_mfma_f32_32x32x16_bf16 v[18:33], v[70:73], v[74:77], v[18:33]
	s_add_u32 m0, s14, 0x4400
	s_nop 0
	global_load_lds_dwordx4 v[150:151], off offset:1024
	s_add_u32 m0, s14, 0x5400
	s_nop 0
	global_load_lds_dwordx4 v[154:155], off offset:1024
	v_mfma_f32_32x32x16_bf16 v[2:17], v[70:73], v[78:81], v[2:17]
	s_add_u32 m0, s14, 0x6400
	s_nop 0
	global_load_lds_dwordx4 v[158:159], off offset:1024
	s_add_u32 m0, s14, 0x7400
	s_nop 0
	global_load_lds_dwordx4 v[162:163], off offset:1024
	s_waitcnt vmcnt(8)
	s_barrier
	ds_read_b128 v[66:69], v130 offset:34816
	ds_read_b128 v[70:73], v130 offset:38912
	ds_read_b128 v[74:77], v134 offset:34816
	ds_read_b128 v[78:81], v134 offset:38912
	v_mfma_f32_32x32x16_bf16 v[50:65], v[82:85], v[90:93], v[50:65]
	v_mfma_f32_32x32x16_bf16 v[34:49], v[82:85], v[94:97], v[34:49]
	v_mfma_f32_32x32x16_bf16 v[18:33], v[86:89], v[90:93], v[18:33]
	v_mfma_f32_32x32x16_bf16 v[2:17], v[86:89], v[94:97], v[2:17]
	ds_read_b128 v[82:85], v131 offset:34816
	ds_read_b128 v[86:89], v131 offset:38912
	ds_read_b128 v[90:93], v135 offset:34816
	ds_read_b128 v[94:97], v135 offset:38912
	v_mfma_f32_32x32x16_bf16 v[50:65], v[98:101], v[106:109], v[50:65]
	v_mfma_f32_32x32x16_bf16 v[34:49], v[98:101], v[110:113], v[34:49]
	v_mfma_f32_32x32x16_bf16 v[18:33], v[102:105], v[106:109], v[18:33]
	v_mfma_f32_32x32x16_bf16 v[2:17], v[102:105], v[110:113], v[2:17]
	ds_read_b128 v[98:101], v132 offset:34816
	ds_read_b128 v[102:105], v132 offset:38912
	ds_read_b128 v[106:109], v136 offset:34816
	ds_read_b128 v[110:113], v136 offset:38912
	v_mfma_f32_32x32x16_bf16 v[50:65], v[114:117], v[122:125], v[50:65]
	v_mfma_f32_32x32x16_bf16 v[34:49], v[114:117], v[126:129], v[34:49]
	v_mfma_f32_32x32x16_bf16 v[18:33], v[118:121], v[122:125], v[18:33]
	v_mfma_f32_32x32x16_bf16 v[2:17], v[118:121], v[126:129], v[2:17]
	ds_read_b128 v[114:117], v133 offset:34816
	ds_read_b128 v[118:121], v133 offset:38912
	ds_read_b128 v[122:125], v137 offset:34816
	ds_read_b128 v[126:129], v137 offset:38912
	s_waitcnt lgkmcnt(0)
	s_barrier
	v_mfma_f32_32x32x16_bf16 v[50:65], v[66:69], v[74:77], v[50:65]
	s_add_u32 m0, s14, 0x8380
	s_nop 0
	global_load_lds_dwordx4 v[148:149], off offset:1152
	s_add_u32 m0, s14, 0x9380
	s_nop 0
	global_load_lds_dwordx4 v[152:153], off offset:1152
	v_mfma_f32_32x32x16_bf16 v[34:49], v[66:69], v[78:81], v[34:49]
	s_add_u32 m0, s14, 0xa380
	s_nop 0
	global_load_lds_dwordx4 v[156:157], off offset:1152
	s_add_u32 m0, s14, 0xb380
	s_nop 0
	global_load_lds_dwordx4 v[160:161], off offset:1152
	v_mfma_f32_32x32x16_bf16 v[18:33], v[70:73], v[74:77], v[18:33]
	s_add_u32 m0, s14, 0xc380
	s_nop 0
	global_load_lds_dwordx4 v[150:151], off offset:1152
	s_add_u32 m0, s14, 0xd380
	s_nop 0
	global_load_lds_dwordx4 v[154:155], off offset:1152
	v_mfma_f32_32x32x16_bf16 v[2:17], v[70:73], v[78:81], v[2:17]
	s_add_u32 m0, s14, 0xe380
	s_nop 0
	global_load_lds_dwordx4 v[158:159], off offset:1152
	s_add_u32 m0, s14, 0xf380
	s_nop 0
	global_load_lds_dwordx4 v[162:163], off offset:1152
	s_waitcnt vmcnt(8)
	s_barrier
	ds_read_b128 v[66:69], v130 offset:2048
	ds_read_b128 v[70:73], v130 offset:6144
	ds_read_b128 v[74:77], v134 offset:2048
	ds_read_b128 v[78:81], v134 offset:6144
	v_mfma_f32_32x32x16_bf16 v[50:65], v[82:85], v[90:93], v[50:65]
	v_mfma_f32_32x32x16_bf16 v[34:49], v[82:85], v[94:97], v[34:49]
	v_mfma_f32_32x32x16_bf16 v[18:33], v[86:89], v[90:93], v[18:33]
	v_mfma_f32_32x32x16_bf16 v[2:17], v[86:89], v[94:97], v[2:17]
	ds_read_b128 v[82:85], v131 offset:2048
	ds_read_b128 v[86:89], v131 offset:6144
	ds_read_b128 v[90:93], v135 offset:2048
	ds_read_b128 v[94:97], v135 offset:6144
	v_mfma_f32_32x32x16_bf16 v[50:65], v[98:101], v[106:109], v[50:65]
	v_mfma_f32_32x32x16_bf16 v[34:49], v[98:101], v[110:113], v[34:49]
	v_mfma_f32_32x32x16_bf16 v[18:33], v[102:105], v[106:109], v[18:33]
	v_mfma_f32_32x32x16_bf16 v[2:17], v[102:105], v[110:113], v[2:17]
	ds_read_b128 v[98:101], v132 offset:2048
	ds_read_b128 v[102:105], v132 offset:6144
	ds_read_b128 v[106:109], v136 offset:2048
	ds_read_b128 v[110:113], v136 offset:6144
	v_mfma_f32_32x32x16_bf16 v[50:65], v[114:117], v[122:125], v[50:65]
	v_mfma_f32_32x32x16_bf16 v[34:49], v[114:117], v[126:129], v[34:49]
	v_mfma_f32_32x32x16_bf16 v[18:33], v[118:121], v[122:125], v[18:33]
	v_mfma_f32_32x32x16_bf16 v[2:17], v[118:121], v[126:129], v[2:17]
	ds_read_b128 v[114:117], v133 offset:2048
	ds_read_b128 v[118:121], v133 offset:6144
	ds_read_b128 v[122:125], v137 offset:2048
	ds_read_b128 v[126:129], v137 offset:6144
	s_waitcnt lgkmcnt(0)
	s_barrier
	v_mfma_f32_32x32x16_bf16 v[50:65], v[66:69], v[74:77], v[50:65]
	s_add_u32 m0, s14, 0x300
	s_nop 0
	global_load_lds_dwordx4 v[148:149], off offset:1280
	s_add_u32 m0, s14, 0x1300
	s_nop 0
	global_load_lds_dwordx4 v[152:153], off offset:1280
	v_mfma_f32_32x32x16_bf16 v[34:49], v[66:69], v[78:81], v[34:49]
	s_add_u32 m0, s14, 0x2300
	s_nop 0
	global_load_lds_dwordx4 v[156:157], off offset:1280
	s_add_u32 m0, s14, 0x3300
	s_nop 0
	global_load_lds_dwordx4 v[160:161], off offset:1280
	v_mfma_f32_32x32x16_bf16 v[18:33], v[70:73], v[74:77], v[18:33]
	s_add_u32 m0, s14, 0x4300
	s_nop 0
	global_load_lds_dwordx4 v[150:151], off offset:1280
	s_add_u32 m0, s14, 0x5300
	s_nop 0
	global_load_lds_dwordx4 v[154:155], off offset:1280
	v_mfma_f32_32x32x16_bf16 v[2:17], v[70:73], v[78:81], v[2:17]
	s_add_u32 m0, s14, 0x6300
	s_nop 0
	global_load_lds_dwordx4 v[158:159], off offset:1280
	s_add_u32 m0, s14, 0x7300
	s_nop 0
	global_load_lds_dwordx4 v[162:163], off offset:1280
	s_waitcnt vmcnt(8)
	s_barrier
	ds_read_b128 v[66:69], v130 offset:34816
	ds_read_b128 v[70:73], v130 offset:38912
	ds_read_b128 v[74:77], v134 offset:34816
	ds_read_b128 v[78:81], v134 offset:38912
	v_mfma_f32_32x32x16_bf16 v[50:65], v[82:85], v[90:93], v[50:65]
	v_mfma_f32_32x32x16_bf16 v[34:49], v[82:85], v[94:97], v[34:49]
	v_mfma_f32_32x32x16_bf16 v[18:33], v[86:89], v[90:93], v[18:33]
	v_mfma_f32_32x32x16_bf16 v[2:17], v[86:89], v[94:97], v[2:17]
	ds_read_b128 v[82:85], v131 offset:34816
	ds_read_b128 v[86:89], v131 offset:38912
	ds_read_b128 v[90:93], v135 offset:34816
	ds_read_b128 v[94:97], v135 offset:38912
	v_mfma_f32_32x32x16_bf16 v[50:65], v[98:101], v[106:109], v[50:65]
	v_mfma_f32_32x32x16_bf16 v[34:49], v[98:101], v[110:113], v[34:49]
	v_mfma_f32_32x32x16_bf16 v[18:33], v[102:105], v[106:109], v[18:33]
	v_mfma_f32_32x32x16_bf16 v[2:17], v[102:105], v[110:113], v[2:17]
	ds_read_b128 v[98:101], v132 offset:34816
	ds_read_b128 v[102:105], v132 offset:38912
	ds_read_b128 v[106:109], v136 offset:34816
	ds_read_b128 v[110:113], v136 offset:38912
	v_mfma_f32_32x32x16_bf16 v[50:65], v[114:117], v[122:125], v[50:65]
	v_mfma_f32_32x32x16_bf16 v[34:49], v[114:117], v[126:129], v[34:49]
	v_mfma_f32_32x32x16_bf16 v[18:33], v[118:121], v[122:125], v[18:33]
	v_mfma_f32_32x32x16_bf16 v[2:17], v[118:121], v[126:129], v[2:17]
	ds_read_b128 v[114:117], v133 offset:34816
	ds_read_b128 v[118:121], v133 offset:38912
	ds_read_b128 v[122:125], v137 offset:34816
	ds_read_b128 v[126:129], v137 offset:38912
	s_waitcnt lgkmcnt(0)
	s_barrier
	v_mfma_f32_32x32x16_bf16 v[50:65], v[66:69], v[74:77], v[50:65]
	s_add_u32 m0, s14, 0x8280
	s_nop 0
	global_load_lds_dwordx4 v[148:149], off offset:1408
	s_add_u32 m0, s14, 0x9280
	s_nop 0
	global_load_lds_dwordx4 v[152:153], off offset:1408
	v_mfma_f32_32x32x16_bf16 v[34:49], v[66:69], v[78:81], v[34:49]
	s_add_u32 m0, s14, 0xa280
	s_nop 0
	global_load_lds_dwordx4 v[156:157], off offset:1408
	s_add_u32 m0, s14, 0xb280
	s_nop 0
	global_load_lds_dwordx4 v[160:161], off offset:1408
	v_mfma_f32_32x32x16_bf16 v[18:33], v[70:73], v[74:77], v[18:33]
	s_add_u32 m0, s14, 0xc280
	s_nop 0
	global_load_lds_dwordx4 v[150:151], off offset:1408
	s_add_u32 m0, s14, 0xd280
	s_nop 0
	global_load_lds_dwordx4 v[154:155], off offset:1408
	v_mfma_f32_32x32x16_bf16 v[2:17], v[70:73], v[78:81], v[2:17]
	s_add_u32 m0, s14, 0xe280
	s_nop 0
	global_load_lds_dwordx4 v[158:159], off offset:1408
	s_add_u32 m0, s14, 0xf280
	s_nop 0
	global_load_lds_dwordx4 v[162:163], off offset:1408
	s_waitcnt vmcnt(8)
	s_barrier
	ds_read_b128 v[66:69], v130 offset:2048
	ds_read_b128 v[70:73], v130 offset:6144
	ds_read_b128 v[74:77], v134 offset:2048
	ds_read_b128 v[78:81], v134 offset:6144
	v_mfma_f32_32x32x16_bf16 v[50:65], v[82:85], v[90:93], v[50:65]
	v_mfma_f32_32x32x16_bf16 v[34:49], v[82:85], v[94:97], v[34:49]
	v_mfma_f32_32x32x16_bf16 v[18:33], v[86:89], v[90:93], v[18:33]
	v_mfma_f32_32x32x16_bf16 v[2:17], v[86:89], v[94:97], v[2:17]
	ds_read_b128 v[82:85], v131 offset:2048
	ds_read_b128 v[86:89], v131 offset:6144
	ds_read_b128 v[90:93], v135 offset:2048
	ds_read_b128 v[94:97], v135 offset:6144
	v_mfma_f32_32x32x16_bf16 v[50:65], v[98:101], v[106:109], v[50:65]
	v_mfma_f32_32x32x16_bf16 v[34:49], v[98:101], v[110:113], v[34:49]
	v_mfma_f32_32x32x16_bf16 v[18:33], v[102:105], v[106:109], v[18:33]
	v_mfma_f32_32x32x16_bf16 v[2:17], v[102:105], v[110:113], v[2:17]
	ds_read_b128 v[98:101], v132 offset:2048
	ds_read_b128 v[102:105], v132 offset:6144
	ds_read_b128 v[106:109], v136 offset:2048
	ds_read_b128 v[110:113], v136 offset:6144
	v_mfma_f32_32x32x16_bf16 v[50:65], v[114:117], v[122:125], v[50:65]
	v_mfma_f32_32x32x16_bf16 v[34:49], v[114:117], v[126:129], v[34:49]
	v_mfma_f32_32x32x16_bf16 v[18:33], v[118:121], v[122:125], v[18:33]
	v_mfma_f32_32x32x16_bf16 v[2:17], v[118:121], v[126:129], v[2:17]
	ds_read_b128 v[114:117], v133 offset:2048
	ds_read_b128 v[118:121], v133 offset:6144
	ds_read_b128 v[122:125], v137 offset:2048
	ds_read_b128 v[126:129], v137 offset:6144
	s_waitcnt lgkmcnt(0)
	s_barrier
	v_mfma_f32_32x32x16_bf16 v[50:65], v[66:69], v[74:77], v[50:65]
	s_add_u32 m0, s14, 0x200
	s_nop 0
	global_load_lds_dwordx4 v[148:149], off offset:1536
	s_add_u32 m0, s14, 0x1200
	s_nop 0
	global_load_lds_dwordx4 v[152:153], off offset:1536
	v_mfma_f32_32x32x16_bf16 v[34:49], v[66:69], v[78:81], v[34:49]
	s_add_u32 m0, s14, 0x2200
	s_nop 0
	global_load_lds_dwordx4 v[156:157], off offset:1536
	s_add_u32 m0, s14, 0x3200
	s_nop 0
	global_load_lds_dwordx4 v[160:161], off offset:1536
	v_mfma_f32_32x32x16_bf16 v[18:33], v[70:73], v[74:77], v[18:33]
	s_add_u32 m0, s14, 0x4200
	s_nop 0
	global_load_lds_dwordx4 v[150:151], off offset:1536
	s_add_u32 m0, s14, 0x5200
	s_nop 0
	global_load_lds_dwordx4 v[154:155], off offset:1536
	v_mfma_f32_32x32x16_bf16 v[2:17], v[70:73], v[78:81], v[2:17]
	s_add_u32 m0, s14, 0x6200
	s_nop 0
	global_load_lds_dwordx4 v[158:159], off offset:1536
	s_add_u32 m0, s14, 0x7200
	s_nop 0
	global_load_lds_dwordx4 v[162:163], off offset:1536
	s_waitcnt vmcnt(8)
	s_barrier
	ds_read_b128 v[66:69], v130 offset:34816
	ds_read_b128 v[70:73], v130 offset:38912
	ds_read_b128 v[74:77], v134 offset:34816
	ds_read_b128 v[78:81], v134 offset:38912
	v_mfma_f32_32x32x16_bf16 v[50:65], v[82:85], v[90:93], v[50:65]
	v_mfma_f32_32x32x16_bf16 v[34:49], v[82:85], v[94:97], v[34:49]
	v_mfma_f32_32x32x16_bf16 v[18:33], v[86:89], v[90:93], v[18:33]
	v_mfma_f32_32x32x16_bf16 v[2:17], v[86:89], v[94:97], v[2:17]
	ds_read_b128 v[82:85], v131 offset:34816
	ds_read_b128 v[86:89], v131 offset:38912
	ds_read_b128 v[90:93], v135 offset:34816
	ds_read_b128 v[94:97], v135 offset:38912
	v_mfma_f32_32x32x16_bf16 v[50:65], v[98:101], v[106:109], v[50:65]
	v_mfma_f32_32x32x16_bf16 v[34:49], v[98:101], v[110:113], v[34:49]
	v_mfma_f32_32x32x16_bf16 v[18:33], v[102:105], v[106:109], v[18:33]
	v_mfma_f32_32x32x16_bf16 v[2:17], v[102:105], v[110:113], v[2:17]
	ds_read_b128 v[98:101], v132 offset:34816
	ds_read_b128 v[102:105], v132 offset:38912
	ds_read_b128 v[106:109], v136 offset:34816
	ds_read_b128 v[110:113], v136 offset:38912
	v_mfma_f32_32x32x16_bf16 v[50:65], v[114:117], v[122:125], v[50:65]
	v_mfma_f32_32x32x16_bf16 v[34:49], v[114:117], v[126:129], v[34:49]
	v_mfma_f32_32x32x16_bf16 v[18:33], v[118:121], v[122:125], v[18:33]
	v_mfma_f32_32x32x16_bf16 v[2:17], v[118:121], v[126:129], v[2:17]
	ds_read_b128 v[114:117], v133 offset:34816
	ds_read_b128 v[118:121], v133 offset:38912
	ds_read_b128 v[122:125], v137 offset:34816
	ds_read_b128 v[126:129], v137 offset:38912
	s_waitcnt lgkmcnt(0)
	s_barrier
	v_mfma_f32_32x32x16_bf16 v[50:65], v[66:69], v[74:77], v[50:65]
	s_add_u32 m0, s14, 0x8180
	s_nop 0
	global_load_lds_dwordx4 v[148:149], off offset:1664
	s_add_u32 m0, s14, 0x9180
	s_nop 0
	global_load_lds_dwordx4 v[152:153], off offset:1664
	v_mfma_f32_32x32x16_bf16 v[34:49], v[66:69], v[78:81], v[34:49]
	s_add_u32 m0, s14, 0xa180
	s_nop 0
	global_load_lds_dwordx4 v[156:157], off offset:1664
	s_add_u32 m0, s14, 0xb180
	s_nop 0
	global_load_lds_dwordx4 v[160:161], off offset:1664
	v_mfma_f32_32x32x16_bf16 v[18:33], v[70:73], v[74:77], v[18:33]
	s_add_u32 m0, s14, 0xc180
	s_nop 0
	global_load_lds_dwordx4 v[150:151], off offset:1664
	s_add_u32 m0, s14, 0xd180
	s_nop 0
	global_load_lds_dwordx4 v[154:155], off offset:1664
	v_mfma_f32_32x32x16_bf16 v[2:17], v[70:73], v[78:81], v[2:17]
	s_add_u32 m0, s14, 0xe180
	s_nop 0
	global_load_lds_dwordx4 v[158:159], off offset:1664
	s_add_u32 m0, s14, 0xf180
	s_nop 0
	global_load_lds_dwordx4 v[162:163], off offset:1664
	s_waitcnt vmcnt(8)
	s_barrier
	ds_read_b128 v[66:69], v130 offset:2048
	ds_read_b128 v[70:73], v130 offset:6144
	ds_read_b128 v[74:77], v134 offset:2048
	ds_read_b128 v[78:81], v134 offset:6144
	v_mfma_f32_32x32x16_bf16 v[50:65], v[82:85], v[90:93], v[50:65]
	v_mfma_f32_32x32x16_bf16 v[34:49], v[82:85], v[94:97], v[34:49]
	v_mfma_f32_32x32x16_bf16 v[18:33], v[86:89], v[90:93], v[18:33]
	v_mfma_f32_32x32x16_bf16 v[2:17], v[86:89], v[94:97], v[2:17]
	ds_read_b128 v[82:85], v131 offset:2048
	ds_read_b128 v[86:89], v131 offset:6144
	ds_read_b128 v[90:93], v135 offset:2048
	ds_read_b128 v[94:97], v135 offset:6144
	v_mfma_f32_32x32x16_bf16 v[50:65], v[98:101], v[106:109], v[50:65]
	v_mfma_f32_32x32x16_bf16 v[34:49], v[98:101], v[110:113], v[34:49]
	v_mfma_f32_32x32x16_bf16 v[18:33], v[102:105], v[106:109], v[18:33]
	v_mfma_f32_32x32x16_bf16 v[2:17], v[102:105], v[110:113], v[2:17]
	ds_read_b128 v[98:101], v132 offset:2048
	ds_read_b128 v[102:105], v132 offset:6144
	ds_read_b128 v[106:109], v136 offset:2048
	ds_read_b128 v[110:113], v136 offset:6144
	v_mfma_f32_32x32x16_bf16 v[50:65], v[114:117], v[122:125], v[50:65]
	v_mfma_f32_32x32x16_bf16 v[34:49], v[114:117], v[126:129], v[34:49]
	v_mfma_f32_32x32x16_bf16 v[18:33], v[118:121], v[122:125], v[18:33]
	v_mfma_f32_32x32x16_bf16 v[2:17], v[118:121], v[126:129], v[2:17]
	ds_read_b128 v[114:117], v133 offset:2048
	ds_read_b128 v[118:121], v133 offset:6144
	ds_read_b128 v[122:125], v137 offset:2048
	ds_read_b128 v[126:129], v137 offset:6144
	s_waitcnt lgkmcnt(0)
	s_barrier
	v_mfma_f32_32x32x16_bf16 v[50:65], v[66:69], v[74:77], v[50:65]
	s_add_u32 m0, s14, 0x100
	s_nop 0
	global_load_lds_dwordx4 v[148:149], off offset:1792
	s_add_u32 m0, s14, 0x1100
	s_nop 0
	global_load_lds_dwordx4 v[152:153], off offset:1792
	v_mfma_f32_32x32x16_bf16 v[34:49], v[66:69], v[78:81], v[34:49]
	s_add_u32 m0, s14, 0x2100
	s_nop 0
	global_load_lds_dwordx4 v[156:157], off offset:1792
	s_add_u32 m0, s14, 0x3100
	s_nop 0
	global_load_lds_dwordx4 v[160:161], off offset:1792
	v_mfma_f32_32x32x16_bf16 v[18:33], v[70:73], v[74:77], v[18:33]
	s_add_u32 m0, s14, 0x4100
	s_nop 0
	global_load_lds_dwordx4 v[150:151], off offset:1792
	s_add_u32 m0, s14, 0x5100
	s_nop 0
	global_load_lds_dwordx4 v[154:155], off offset:1792
	v_mfma_f32_32x32x16_bf16 v[2:17], v[70:73], v[78:81], v[2:17]
	s_add_u32 m0, s14, 0x6100
	s_nop 0
	global_load_lds_dwordx4 v[158:159], off offset:1792
	s_add_u32 m0, s14, 0x7100
	s_nop 0
	global_load_lds_dwordx4 v[162:163], off offset:1792
	s_waitcnt vmcnt(8)
	s_barrier
	ds_read_b128 v[66:69], v130 offset:34816
	ds_read_b128 v[70:73], v130 offset:38912
	ds_read_b128 v[74:77], v134 offset:34816
	ds_read_b128 v[78:81], v134 offset:38912
	v_mfma_f32_32x32x16_bf16 v[50:65], v[82:85], v[90:93], v[50:65]
	v_mfma_f32_32x32x16_bf16 v[34:49], v[82:85], v[94:97], v[34:49]
	v_mfma_f32_32x32x16_bf16 v[18:33], v[86:89], v[90:93], v[18:33]
	v_mfma_f32_32x32x16_bf16 v[2:17], v[86:89], v[94:97], v[2:17]
	ds_read_b128 v[82:85], v131 offset:34816
	ds_read_b128 v[86:89], v131 offset:38912
	ds_read_b128 v[90:93], v135 offset:34816
	ds_read_b128 v[94:97], v135 offset:38912
	v_mfma_f32_32x32x16_bf16 v[50:65], v[98:101], v[106:109], v[50:65]
	v_mfma_f32_32x32x16_bf16 v[34:49], v[98:101], v[110:113], v[34:49]
	v_mfma_f32_32x32x16_bf16 v[18:33], v[102:105], v[106:109], v[18:33]
	v_mfma_f32_32x32x16_bf16 v[2:17], v[102:105], v[110:113], v[2:17]
	ds_read_b128 v[98:101], v132 offset:34816
	ds_read_b128 v[102:105], v132 offset:38912
	ds_read_b128 v[106:109], v136 offset:34816
	ds_read_b128 v[110:113], v136 offset:38912
	v_mfma_f32_32x32x16_bf16 v[50:65], v[114:117], v[122:125], v[50:65]
	v_mfma_f32_32x32x16_bf16 v[34:49], v[114:117], v[126:129], v[34:49]
	v_mfma_f32_32x32x16_bf16 v[18:33], v[118:121], v[122:125], v[18:33]
	v_mfma_f32_32x32x16_bf16 v[2:17], v[118:121], v[126:129], v[2:17]
	ds_read_b128 v[114:117], v133 offset:34816
	ds_read_b128 v[118:121], v133 offset:38912
	ds_read_b128 v[122:125], v137 offset:34816
	ds_read_b128 v[126:129], v137 offset:38912
	s_waitcnt lgkmcnt(0)
	s_barrier
	v_mfma_f32_32x32x16_bf16 v[50:65], v[66:69], v[74:77], v[50:65]
	s_add_u32 m0, s14, 0x8080
	s_nop 0
	global_load_lds_dwordx4 v[148:149], off offset:1920
	s_add_u32 m0, s14, 0x9080
	s_nop 0
	global_load_lds_dwordx4 v[152:153], off offset:1920
	v_mfma_f32_32x32x16_bf16 v[34:49], v[66:69], v[78:81], v[34:49]
	s_add_u32 m0, s14, 0xa080
	s_nop 0
	global_load_lds_dwordx4 v[156:157], off offset:1920
	s_add_u32 m0, s14, 0xb080
	s_nop 0
	global_load_lds_dwordx4 v[160:161], off offset:1920
	v_mfma_f32_32x32x16_bf16 v[18:33], v[70:73], v[74:77], v[18:33]
	s_add_u32 m0, s14, 0xc080
	s_nop 0
	global_load_lds_dwordx4 v[150:151], off offset:1920
	s_add_u32 m0, s14, 0xd080
	s_nop 0
	global_load_lds_dwordx4 v[154:155], off offset:1920
	v_mfma_f32_32x32x16_bf16 v[2:17], v[70:73], v[78:81], v[2:17]
	s_add_u32 m0, s14, 0xe080
	s_nop 0
	global_load_lds_dwordx4 v[158:159], off offset:1920
	s_add_u32 m0, s14, 0xf080
	s_nop 0
	global_load_lds_dwordx4 v[162:163], off offset:1920
	s_waitcnt vmcnt(8)
	s_barrier
	ds_read_b128 v[66:69], v130 offset:2048
	ds_read_b128 v[70:73], v130 offset:6144
	ds_read_b128 v[74:77], v134 offset:2048
	ds_read_b128 v[78:81], v134 offset:6144
	v_mfma_f32_32x32x16_bf16 v[50:65], v[82:85], v[90:93], v[50:65]
	v_mfma_f32_32x32x16_bf16 v[34:49], v[82:85], v[94:97], v[34:49]
	v_mfma_f32_32x32x16_bf16 v[18:33], v[86:89], v[90:93], v[18:33]
	v_mfma_f32_32x32x16_bf16 v[2:17], v[86:89], v[94:97], v[2:17]
	ds_read_b128 v[82:85], v131 offset:2048
	ds_read_b128 v[86:89], v131 offset:6144
	ds_read_b128 v[90:93], v135 offset:2048
	ds_read_b128 v[94:97], v135 offset:6144
	v_mfma_f32_32x32x16_bf16 v[50:65], v[98:101], v[106:109], v[50:65]
	v_mfma_f32_32x32x16_bf16 v[34:49], v[98:101], v[110:113], v[34:49]
	v_mfma_f32_32x32x16_bf16 v[18:33], v[102:105], v[106:109], v[18:33]
	v_mfma_f32_32x32x16_bf16 v[2:17], v[102:105], v[110:113], v[2:17]
	ds_read_b128 v[98:101], v132 offset:2048
	ds_read_b128 v[102:105], v132 offset:6144
	ds_read_b128 v[106:109], v136 offset:2048
	ds_read_b128 v[110:113], v136 offset:6144
	v_mfma_f32_32x32x16_bf16 v[50:65], v[114:117], v[122:125], v[50:65]
	v_mfma_f32_32x32x16_bf16 v[34:49], v[114:117], v[126:129], v[34:49]
	v_mfma_f32_32x32x16_bf16 v[18:33], v[118:121], v[122:125], v[18:33]
	v_mfma_f32_32x32x16_bf16 v[2:17], v[118:121], v[126:129], v[2:17]
	ds_read_b128 v[114:117], v133 offset:2048
	ds_read_b128 v[118:121], v133 offset:6144
	ds_read_b128 v[122:125], v137 offset:2048
	ds_read_b128 v[126:129], v137 offset:6144
	s_waitcnt lgkmcnt(0)
	v_mfma_f32_32x32x16_bf16 v[50:65], v[66:69], v[74:77], v[50:65]
	v_mfma_f32_32x32x16_bf16 v[34:49], v[66:69], v[78:81], v[34:49]
	v_mfma_f32_32x32x16_bf16 v[18:33], v[70:73], v[74:77], v[18:33]
	v_mfma_f32_32x32x16_bf16 v[2:17], v[70:73], v[78:81], v[2:17]
	s_waitcnt vmcnt(0)
	s_barrier
	ds_read_b128 v[66:69], v130 offset:34816
	ds_read_b128 v[70:73], v130 offset:38912
	ds_read_b128 v[74:77], v134 offset:34816
	ds_read_b128 v[78:81], v134 offset:38912
	v_mfma_f32_32x32x16_bf16 v[50:65], v[82:85], v[90:93], v[50:65]
	v_mfma_f32_32x32x16_bf16 v[34:49], v[82:85], v[94:97], v[34:49]
	v_mfma_f32_32x32x16_bf16 v[18:33], v[86:89], v[90:93], v[18:33]
	v_mfma_f32_32x32x16_bf16 v[2:17], v[86:89], v[94:97], v[2:17]
	ds_read_b128 v[82:85], v131 offset:34816
	ds_read_b128 v[86:89], v131 offset:38912
	ds_read_b128 v[90:93], v135 offset:34816
	ds_read_b128 v[94:97], v135 offset:38912
	v_mfma_f32_32x32x16_bf16 v[50:65], v[98:101], v[106:109], v[50:65]
	v_mfma_f32_32x32x16_bf16 v[34:49], v[98:101], v[110:113], v[34:49]
	v_mfma_f32_32x32x16_bf16 v[18:33], v[102:105], v[106:109], v[18:33]
	v_mfma_f32_32x32x16_bf16 v[2:17], v[102:105], v[110:113], v[2:17]
	ds_read_b128 v[98:101], v132 offset:34816
	ds_read_b128 v[102:105], v132 offset:38912
	ds_read_b128 v[106:109], v136 offset:34816
	ds_read_b128 v[110:113], v136 offset:38912
	v_mfma_f32_32x32x16_bf16 v[50:65], v[114:117], v[122:125], v[50:65]
	v_mfma_f32_32x32x16_bf16 v[34:49], v[114:117], v[126:129], v[34:49]
	v_mfma_f32_32x32x16_bf16 v[18:33], v[118:121], v[122:125], v[18:33]
	v_mfma_f32_32x32x16_bf16 v[2:17], v[118:121], v[126:129], v[2:17]
	ds_read_b128 v[114:117], v133 offset:34816
	ds_read_b128 v[118:121], v133 offset:38912
	ds_read_b128 v[122:125], v137 offset:34816
	ds_read_b128 v[126:129], v137 offset:38912
	s_waitcnt lgkmcnt(0)
	v_mfma_f32_32x32x16_bf16 v[50:65], v[66:69], v[74:77], v[50:65]
	v_mfma_f32_32x32x16_bf16 v[34:49], v[66:69], v[78:81], v[34:49]
	v_mfma_f32_32x32x16_bf16 v[18:33], v[70:73], v[74:77], v[18:33]
	v_mfma_f32_32x32x16_bf16 v[2:17], v[70:73], v[78:81], v[2:17]
	v_mfma_f32_32x32x16_bf16 v[50:65], v[82:85], v[90:93], v[50:65]
	v_mfma_f32_32x32x16_bf16 v[34:49], v[82:85], v[94:97], v[34:49]
	v_mfma_f32_32x32x16_bf16 v[18:33], v[86:89], v[90:93], v[18:33]
	v_mfma_f32_32x32x16_bf16 v[2:17], v[86:89], v[94:97], v[2:17]
	v_mfma_f32_32x32x16_bf16 v[50:65], v[98:101], v[106:109], v[50:65]
	v_mfma_f32_32x32x16_bf16 v[34:49], v[98:101], v[110:113], v[34:49]
	v_mfma_f32_32x32x16_bf16 v[18:33], v[102:105], v[106:109], v[18:33]
	v_mfma_f32_32x32x16_bf16 v[2:17], v[102:105], v[110:113], v[2:17]
	v_mfma_f32_32x32x16_bf16 v[50:65], v[114:117], v[122:125], v[50:65]
	v_mfma_f32_32x32x16_bf16 v[34:49], v[114:117], v[126:129], v[34:49]
	v_mfma_f32_32x32x16_bf16 v[18:33], v[118:121], v[122:125], v[18:33]
	v_mfma_f32_32x32x16_bf16 v[2:17], v[118:121], v[126:129], v[2:17]
	s_setprio 0
	s_cmp_eq_u32 s45, 1
	s_waitcnt lgkmcnt(0)
	s_barrier
	s_nop 0
	s_nop 0
	s_nop 10
	v_mul_f32_e32 v0, 0xbfb8aa3b, v50
	v_exp_f32_e32 v0, v0
	s_nop 0
	v_add_f32_e32 v0, 1.0, v0
	v_div_scale_f32 v50, s[0:1], v0, v0, 1.0
	v_rcp_f32_e32 v66, v50
	s_nop 0
	v_fma_f32 v67, -v50, v66, 1.0
	v_fmac_f32_e32 v66, v67, v66
	v_div_scale_f32 v67, vcc, 1.0, v0, 1.0
	v_mul_f32_e32 v68, v67, v66
	v_fma_f32 v69, -v50, v68, v67
	v_fmac_f32_e32 v68, v69, v66
	v_fma_f32 v50, -v50, v68, v67
	v_div_fmas_f32 v50, v50, v66, v68
	v_div_fixup_f32 v0, v50, v0, 1.0
	v_fma_f32 v0, v0, s80, 0.5
	v_cvt_u32_f32_e32 v116, v0
	v_mul_f32_e32 v0, 0xbfb8aa3b, v51
	v_exp_f32_e32 v0, v0
	s_nop 0
	v_add_f32_e32 v0, 1.0, v0
	v_div_scale_f32 v50, s[0:1], v0, v0, 1.0
	v_rcp_f32_e32 v51, v50
	s_nop 0
	v_fma_f32 v66, -v50, v51, 1.0
	v_fmac_f32_e32 v51, v66, v51
	v_div_scale_f32 v66, vcc, 1.0, v0, 1.0
	v_mul_f32_e32 v67, v66, v51
	v_fma_f32 v68, -v50, v67, v66
	v_fmac_f32_e32 v67, v68, v51
	v_fma_f32 v50, -v50, v67, v66
	v_div_fmas_f32 v50, v50, v51, v67
	v_div_fixup_f32 v0, v50, v0, 1.0
	v_mul_f32_e32 v50, 0xbfb8aa3b, v52
	v_exp_f32_e32 v50, v50
	v_fma_f32 v0, v0, s80, 0.5
	v_cvt_u32_f32_e32 v0, v0
	v_add_f32_e32 v50, 1.0, v50
	v_div_scale_f32 v51, s[0:1], v50, v50, 1.0
	v_rcp_f32_e32 v52, v51
	v_lshl_or_b32 v118, v0, 8, v116
	v_mul_f32_e32 v0, 0xbfb8aa3b, v54
	v_exp_f32_e32 v0, v0
	v_fma_f32 v66, -v51, v52, 1.0
	v_fmac_f32_e32 v52, v66, v52
	v_div_scale_f32 v66, vcc, 1.0, v50, 1.0
	v_mul_f32_e32 v67, v66, v52
	v_fma_f32 v68, -v51, v67, v66
	v_fmac_f32_e32 v67, v68, v52
	v_fma_f32 v51, -v51, v67, v66
	v_div_fmas_f32 v51, v51, v52, v67
	v_div_fixup_f32 v50, v51, v50, 1.0
	v_mul_f32_e32 v51, 0xbfb8aa3b, v53
	v_exp_f32_e32 v51, v51
	v_fma_f32 v50, v50, s80, 0.5
	v_cvt_u32_f32_sdwa v50, v50 dst_sel:WORD_1 dst_unused:UNUSED_PAD src0_sel:DWORD
	v_add_f32_e32 v0, 1.0, v0
	v_add_f32_e32 v51, 1.0, v51
	v_div_scale_f32 v52, s[0:1], v51, v51, 1.0
	v_rcp_f32_e32 v53, v52
	s_nop 0
	v_fma_f32 v66, -v52, v53, 1.0
	v_fmac_f32_e32 v53, v66, v53
	v_div_scale_f32 v66, vcc, 1.0, v51, 1.0
	v_mul_f32_e32 v67, v66, v53
	v_fma_f32 v68, -v52, v67, v66
	v_fmac_f32_e32 v67, v68, v53
	v_fma_f32 v52, -v52, v67, v66
	v_div_fmas_f32 v52, v52, v53, v67
	v_div_fixup_f32 v51, v52, v51, 1.0
	v_fma_f32 v51, v51, s80, 0.5
	v_cvt_u32_f32_sdwa v51, v51 dst_sel:BYTE_3 dst_unused:UNUSED_PAD src0_sel:DWORD
	s_nop 0
	v_or3_b32 v117, v50, v51, v118
	v_div_scale_f32 v50, s[0:1], v0, v0, 1.0
	v_rcp_f32_e32 v51, v50
	s_nop 0
	v_fma_f32 v52, -v50, v51, 1.0
	v_fmac_f32_e32 v51, v52, v51
	v_div_scale_f32 v52, vcc, 1.0, v0, 1.0
	v_mul_f32_e32 v53, v52, v51
	v_fma_f32 v54, -v50, v53, v52
	v_fmac_f32_e32 v53, v54, v51
	v_fma_f32 v50, -v50, v53, v52
	v_div_fmas_f32 v50, v50, v51, v53
	v_div_fixup_f32 v0, v50, v0, 1.0
	v_fma_f32 v0, v0, s80, 0.5
	v_cvt_u32_f32_e32 v119, v0
	v_mul_f32_e32 v0, 0xbfb8aa3b, v55
	v_exp_f32_e32 v0, v0
	s_nop 0
	v_add_f32_e32 v0, 1.0, v0
	v_div_scale_f32 v50, s[0:1], v0, v0, 1.0
	v_rcp_f32_e32 v51, v50
	s_nop 0
	v_fma_f32 v52, -v50, v51, 1.0
	v_fmac_f32_e32 v51, v52, v51
	v_div_scale_f32 v52, vcc, 1.0, v0, 1.0
	v_mul_f32_e32 v53, v52, v51
	v_fma_f32 v54, -v50, v53, v52
	v_fmac_f32_e32 v53, v54, v51
	v_fma_f32 v50, -v50, v53, v52
	v_div_fmas_f32 v50, v50, v51, v53
	v_div_fixup_f32 v0, v50, v0, 1.0
	v_mul_f32_e32 v50, 0xbfb8aa3b, v56
	v_exp_f32_e32 v50, v50
	v_fma_f32 v0, v0, s80, 0.5
	v_cvt_u32_f32_e32 v0, v0
	v_add_f32_e32 v50, 1.0, v50
	v_div_scale_f32 v51, s[0:1], v50, v50, 1.0
	v_rcp_f32_e32 v52, v51
	v_lshl_or_b32 v121, v0, 8, v119
	v_mul_f32_e32 v0, 0xbfb8aa3b, v58
	v_exp_f32_e32 v0, v0
	v_fma_f32 v53, -v51, v52, 1.0
	v_fmac_f32_e32 v52, v53, v52
	v_div_scale_f32 v53, vcc, 1.0, v50, 1.0
	v_mul_f32_e32 v54, v53, v52
	v_fma_f32 v55, -v51, v54, v53
	v_fmac_f32_e32 v54, v55, v52
	v_fma_f32 v51, -v51, v54, v53
	v_div_fmas_f32 v51, v51, v52, v54
	v_div_fixup_f32 v50, v51, v50, 1.0
	v_mul_f32_e32 v51, 0xbfb8aa3b, v57
	v_exp_f32_e32 v51, v51
	v_fma_f32 v50, v50, s80, 0.5
	v_cvt_u32_f32_sdwa v50, v50 dst_sel:WORD_1 dst_unused:UNUSED_PAD src0_sel:DWORD
	v_add_f32_e32 v0, 1.0, v0
	v_add_f32_e32 v51, 1.0, v51
	v_div_scale_f32 v52, s[0:1], v51, v51, 1.0
	v_rcp_f32_e32 v53, v52
	s_nop 0
	v_fma_f32 v54, -v52, v53, 1.0
	v_fmac_f32_e32 v53, v54, v53
	v_div_scale_f32 v54, vcc, 1.0, v51, 1.0
	v_mul_f32_e32 v55, v54, v53
	v_fma_f32 v56, -v52, v55, v54
	v_fmac_f32_e32 v55, v56, v53
	v_fma_f32 v52, -v52, v55, v54
	v_div_fmas_f32 v52, v52, v53, v55
	v_div_fixup_f32 v51, v52, v51, 1.0
	v_fma_f32 v51, v51, s80, 0.5
	v_cvt_u32_f32_sdwa v51, v51 dst_sel:BYTE_3 dst_unused:UNUSED_PAD src0_sel:DWORD
	s_nop 0
	v_or3_b32 v120, v50, v51, v121
	v_div_scale_f32 v50, s[0:1], v0, v0, 1.0
	v_rcp_f32_e32 v51, v50
	s_nop 0
	v_fma_f32 v52, -v50, v51, 1.0
	v_fmac_f32_e32 v51, v52, v51
	v_div_scale_f32 v52, vcc, 1.0, v0, 1.0
	v_mul_f32_e32 v53, v52, v51
	v_fma_f32 v54, -v50, v53, v52
	v_fmac_f32_e32 v53, v54, v51
	v_fma_f32 v50, -v50, v53, v52
	v_div_fmas_f32 v50, v50, v51, v53
	v_div_fixup_f32 v0, v50, v0, 1.0
	v_fma_f32 v0, v0, s80, 0.5
	v_cvt_u32_f32_e32 v122, v0
	v_mul_f32_e32 v0, 0xbfb8aa3b, v59
	v_exp_f32_e32 v0, v0
	s_nop 0
	v_add_f32_e32 v0, 1.0, v0
	v_div_scale_f32 v50, s[0:1], v0, v0, 1.0
	v_rcp_f32_e32 v51, v50
	s_nop 0
	v_fma_f32 v52, -v50, v51, 1.0
	v_fmac_f32_e32 v51, v52, v51
	v_div_scale_f32 v52, vcc, 1.0, v0, 1.0
	v_mul_f32_e32 v53, v52, v51
	v_fma_f32 v54, -v50, v53, v52
	v_fmac_f32_e32 v53, v54, v51
	v_fma_f32 v50, -v50, v53, v52
	v_div_fmas_f32 v50, v50, v51, v53
	v_div_fixup_f32 v0, v50, v0, 1.0
	v_mul_f32_e32 v50, 0xbfb8aa3b, v60
	v_exp_f32_e32 v50, v50
	v_fma_f32 v0, v0, s80, 0.5
	v_cvt_u32_f32_e32 v0, v0
	v_add_f32_e32 v50, 1.0, v50
	v_div_scale_f32 v51, s[0:1], v50, v50, 1.0
	v_rcp_f32_e32 v52, v51
	v_lshl_or_b32 v124, v0, 8, v122
	v_mul_f32_e32 v0, 0xbfb8aa3b, v62
	v_exp_f32_e32 v0, v0
	v_fma_f32 v53, -v51, v52, 1.0
	v_fmac_f32_e32 v52, v53, v52
	v_div_scale_f32 v53, vcc, 1.0, v50, 1.0
	v_mul_f32_e32 v54, v53, v52
	v_fma_f32 v55, -v51, v54, v53
	v_fmac_f32_e32 v54, v55, v52
	v_fma_f32 v51, -v51, v54, v53
	v_div_fmas_f32 v51, v51, v52, v54
	v_div_fixup_f32 v50, v51, v50, 1.0
	v_mul_f32_e32 v51, 0xbfb8aa3b, v61
	v_exp_f32_e32 v51, v51
	v_fma_f32 v50, v50, s80, 0.5
	v_cvt_u32_f32_sdwa v50, v50 dst_sel:WORD_1 dst_unused:UNUSED_PAD src0_sel:DWORD
	v_add_f32_e32 v0, 1.0, v0
	v_add_f32_e32 v51, 1.0, v51
	v_div_scale_f32 v52, s[0:1], v51, v51, 1.0
	v_rcp_f32_e32 v53, v52
	s_nop 0
	v_fma_f32 v54, -v52, v53, 1.0
	v_fmac_f32_e32 v53, v54, v53
	v_div_scale_f32 v54, vcc, 1.0, v51, 1.0
	v_mul_f32_e32 v55, v54, v53
	v_fma_f32 v56, -v52, v55, v54
	v_fmac_f32_e32 v55, v56, v53
	v_fma_f32 v52, -v52, v55, v54
	v_div_fmas_f32 v52, v52, v53, v55
	v_div_fixup_f32 v51, v52, v51, 1.0
	v_fma_f32 v51, v51, s80, 0.5
	v_cvt_u32_f32_sdwa v51, v51 dst_sel:BYTE_3 dst_unused:UNUSED_PAD src0_sel:DWORD
	s_nop 0
	v_or3_b32 v123, v50, v51, v124
	v_div_scale_f32 v50, s[0:1], v0, v0, 1.0
	v_rcp_f32_e32 v51, v50
	s_nop 0
	v_fma_f32 v52, -v50, v51, 1.0
	v_fmac_f32_e32 v51, v52, v51
	v_div_scale_f32 v52, vcc, 1.0, v0, 1.0
	v_mul_f32_e32 v53, v52, v51
	v_fma_f32 v54, -v50, v53, v52
	v_fmac_f32_e32 v53, v54, v51
	v_fma_f32 v50, -v50, v53, v52
	v_div_fmas_f32 v50, v50, v51, v53
	v_div_fixup_f32 v0, v50, v0, 1.0
	v_fma_f32 v0, v0, s80, 0.5
	v_cvt_u32_f32_e32 v125, v0
	v_mul_f32_e32 v0, 0xbfb8aa3b, v63
	v_exp_f32_e32 v0, v0
	s_nop 0
	v_add_f32_e32 v0, 1.0, v0
	v_div_scale_f32 v50, s[0:1], v0, v0, 1.0
	v_rcp_f32_e32 v51, v50
	s_nop 0
	v_fma_f32 v52, -v50, v51, 1.0
	v_fmac_f32_e32 v51, v52, v51
	v_div_scale_f32 v52, vcc, 1.0, v0, 1.0
	v_mul_f32_e32 v53, v52, v51
	v_fma_f32 v54, -v50, v53, v52
	v_fmac_f32_e32 v53, v54, v51
	v_fma_f32 v50, -v50, v53, v52
	v_div_fmas_f32 v50, v50, v51, v53
	v_div_fixup_f32 v0, v50, v0, 1.0
	v_mul_f32_e32 v50, 0xbfb8aa3b, v64
	v_exp_f32_e32 v50, v50
	v_fma_f32 v0, v0, s80, 0.5
	v_cvt_u32_f32_e32 v0, v0
	v_add_f32_e32 v50, 1.0, v50
	v_div_scale_f32 v51, s[0:1], v50, v50, 1.0
	v_rcp_f32_e32 v52, v51
	v_lshl_or_b32 v127, v0, 8, v125
	v_mul_f32_e32 v0, 0xbfb8aa3b, v34
	v_exp_f32_e32 v0, v0
	v_fma_f32 v53, -v51, v52, 1.0
	v_fmac_f32_e32 v52, v53, v52
	v_div_scale_f32 v53, vcc, 1.0, v50, 1.0
	v_mul_f32_e32 v54, v53, v52
	v_fma_f32 v55, -v51, v54, v53
	v_fmac_f32_e32 v54, v55, v52
	v_fma_f32 v51, -v51, v54, v53
	v_div_fmas_f32 v51, v51, v52, v54
	v_div_fixup_f32 v50, v51, v50, 1.0
	v_mul_f32_e32 v51, 0xbfb8aa3b, v65
	v_exp_f32_e32 v51, v51
	v_fma_f32 v50, v50, s80, 0.5
	v_cvt_u32_f32_sdwa v50, v50 dst_sel:WORD_1 dst_unused:UNUSED_PAD src0_sel:DWORD
	v_add_f32_e32 v0, 1.0, v0
	v_add_f32_e32 v51, 1.0, v51
	v_div_scale_f32 v52, s[0:1], v51, v51, 1.0
	v_rcp_f32_e32 v53, v52
	v_div_scale_f32 v34, s[0:1], v0, v0, 1.0
	v_fma_f32 v54, -v52, v53, 1.0
	v_fmac_f32_e32 v53, v54, v53
	v_div_scale_f32 v54, vcc, 1.0, v51, 1.0
	v_mul_f32_e32 v55, v54, v53
	v_fma_f32 v56, -v52, v55, v54
	v_fmac_f32_e32 v55, v56, v53
	v_fma_f32 v52, -v52, v55, v54
	v_div_fmas_f32 v52, v52, v53, v55
	v_div_fixup_f32 v51, v52, v51, 1.0
	v_fma_f32 v51, v51, s80, 0.5
	v_cvt_u32_f32_sdwa v51, v51 dst_sel:BYTE_3 dst_unused:UNUSED_PAD src0_sel:DWORD
	s_nop 0
	v_or3_b32 v126, v50, v51, v127
	v_rcp_f32_e32 v50, v34
	s_nop 0
	v_fma_f32 v51, -v34, v50, 1.0
	v_fmac_f32_e32 v50, v51, v50
	v_div_scale_f32 v51, vcc, 1.0, v0, 1.0
	v_mul_f32_e32 v52, v51, v50
	v_fma_f32 v53, -v34, v52, v51
	v_fmac_f32_e32 v52, v53, v50
	v_fma_f32 v34, -v34, v52, v51
	v_div_fmas_f32 v34, v34, v50, v52
	v_div_fixup_f32 v0, v34, v0, 1.0
	v_fma_f32 v0, v0, s80, 0.5
	v_cvt_u32_f32_e32 v128, v0
	v_mul_f32_e32 v0, 0xbfb8aa3b, v35
	v_exp_f32_e32 v0, v0
	s_nop 0
	v_add_f32_e32 v0, 1.0, v0
	v_div_scale_f32 v34, s[0:1], v0, v0, 1.0
	v_rcp_f32_e32 v35, v34
	s_nop 0
	v_fma_f32 v50, -v34, v35, 1.0
	v_fmac_f32_e32 v35, v50, v35
	v_div_scale_f32 v50, vcc, 1.0, v0, 1.0
	v_mul_f32_e32 v51, v50, v35
	v_fma_f32 v52, -v34, v51, v50
	v_fmac_f32_e32 v51, v52, v35
	v_fma_f32 v34, -v34, v51, v50
	v_div_fmas_f32 v34, v34, v35, v51
	v_div_fixup_f32 v0, v34, v0, 1.0
	v_mul_f32_e32 v34, 0xbfb8aa3b, v36
	v_exp_f32_e32 v34, v34
	v_fma_f32 v0, v0, s80, 0.5
	v_cvt_u32_f32_e32 v0, v0
	v_add_f32_e32 v34, 1.0, v34
	v_div_scale_f32 v35, s[0:1], v34, v34, 1.0
	v_rcp_f32_e32 v36, v35
	v_lshl_or_b32 v130, v0, 8, v128
	v_mul_f32_e32 v0, 0xbfb8aa3b, v38
	v_exp_f32_e32 v0, v0
	v_fma_f32 v50, -v35, v36, 1.0
	v_fmac_f32_e32 v36, v50, v36
	v_div_scale_f32 v50, vcc, 1.0, v34, 1.0
	v_mul_f32_e32 v51, v50, v36
	v_fma_f32 v52, -v35, v51, v50
	v_fmac_f32_e32 v51, v52, v36
	v_fma_f32 v35, -v35, v51, v50
	v_div_fmas_f32 v35, v35, v36, v51
	v_div_fixup_f32 v34, v35, v34, 1.0
	v_mul_f32_e32 v35, 0xbfb8aa3b, v37
	v_exp_f32_e32 v35, v35
	v_fma_f32 v34, v34, s80, 0.5
	v_cvt_u32_f32_sdwa v34, v34 dst_sel:WORD_1 dst_unused:UNUSED_PAD src0_sel:DWORD
	v_add_f32_e32 v0, 1.0, v0
	v_add_f32_e32 v35, 1.0, v35
	v_div_scale_f32 v36, s[0:1], v35, v35, 1.0
	v_rcp_f32_e32 v37, v36
	s_nop 0
	v_fma_f32 v50, -v36, v37, 1.0
	v_fmac_f32_e32 v37, v50, v37
	v_div_scale_f32 v50, vcc, 1.0, v35, 1.0
	v_mul_f32_e32 v51, v50, v37
	v_fma_f32 v52, -v36, v51, v50
	v_fmac_f32_e32 v51, v52, v37
	v_fma_f32 v36, -v36, v51, v50
	v_div_fmas_f32 v36, v36, v37, v51
	v_div_fixup_f32 v35, v36, v35, 1.0
	v_fma_f32 v35, v35, s80, 0.5
	v_cvt_u32_f32_sdwa v35, v35 dst_sel:BYTE_3 dst_unused:UNUSED_PAD src0_sel:DWORD
	s_nop 0
	v_or3_b32 v129, v34, v35, v130
	v_div_scale_f32 v34, s[0:1], v0, v0, 1.0
	v_rcp_f32_e32 v35, v34
	s_nop 0
	v_fma_f32 v36, -v34, v35, 1.0
	v_fmac_f32_e32 v35, v36, v35
	v_div_scale_f32 v36, vcc, 1.0, v0, 1.0
	v_mul_f32_e32 v37, v36, v35
	v_fma_f32 v38, -v34, v37, v36
	v_fmac_f32_e32 v37, v38, v35
	v_fma_f32 v34, -v34, v37, v36
	v_div_fmas_f32 v34, v34, v35, v37
	v_div_fixup_f32 v0, v34, v0, 1.0
	v_fma_f32 v0, v0, s80, 0.5
	v_cvt_u32_f32_e32 v131, v0
	v_mul_f32_e32 v0, 0xbfb8aa3b, v39
	v_exp_f32_e32 v0, v0
	s_nop 0
	v_add_f32_e32 v0, 1.0, v0
	v_div_scale_f32 v34, s[0:1], v0, v0, 1.0
	v_rcp_f32_e32 v35, v34
	s_nop 0
	v_fma_f32 v36, -v34, v35, 1.0
	v_fmac_f32_e32 v35, v36, v35
	v_div_scale_f32 v36, vcc, 1.0, v0, 1.0
	v_mul_f32_e32 v37, v36, v35
	v_fma_f32 v38, -v34, v37, v36
	v_fmac_f32_e32 v37, v38, v35
	v_fma_f32 v34, -v34, v37, v36
	v_div_fmas_f32 v34, v34, v35, v37
	v_div_fixup_f32 v0, v34, v0, 1.0
	v_mul_f32_e32 v34, 0xbfb8aa3b, v40
	v_exp_f32_e32 v34, v34
	v_fma_f32 v0, v0, s80, 0.5
	v_cvt_u32_f32_e32 v0, v0
	v_add_f32_e32 v34, 1.0, v34
	v_div_scale_f32 v35, s[0:1], v34, v34, 1.0
	v_rcp_f32_e32 v36, v35
	v_lshl_or_b32 v133, v0, 8, v131
	v_mul_f32_e32 v0, 0xbfb8aa3b, v42
	v_exp_f32_e32 v0, v0
	v_fma_f32 v37, -v35, v36, 1.0
	v_fmac_f32_e32 v36, v37, v36
	v_div_scale_f32 v37, vcc, 1.0, v34, 1.0
	v_mul_f32_e32 v38, v37, v36
	v_fma_f32 v39, -v35, v38, v37
	v_fmac_f32_e32 v38, v39, v36
	v_fma_f32 v35, -v35, v38, v37
	v_div_fmas_f32 v35, v35, v36, v38
	v_div_fixup_f32 v34, v35, v34, 1.0
	v_mul_f32_e32 v35, 0xbfb8aa3b, v41
	v_exp_f32_e32 v35, v35
	v_fma_f32 v34, v34, s80, 0.5
	v_cvt_u32_f32_sdwa v34, v34 dst_sel:WORD_1 dst_unused:UNUSED_PAD src0_sel:DWORD
	v_add_f32_e32 v0, 1.0, v0
	v_add_f32_e32 v35, 1.0, v35
	v_div_scale_f32 v36, s[0:1], v35, v35, 1.0
	v_rcp_f32_e32 v37, v36
	s_nop 0
	v_fma_f32 v38, -v36, v37, 1.0
	v_fmac_f32_e32 v37, v38, v37
	v_div_scale_f32 v38, vcc, 1.0, v35, 1.0
	v_mul_f32_e32 v39, v38, v37
	v_fma_f32 v40, -v36, v39, v38
	v_fmac_f32_e32 v39, v40, v37
	v_fma_f32 v36, -v36, v39, v38
	v_div_fmas_f32 v36, v36, v37, v39
	v_div_fixup_f32 v35, v36, v35, 1.0
	v_fma_f32 v35, v35, s80, 0.5
	v_cvt_u32_f32_sdwa v35, v35 dst_sel:BYTE_3 dst_unused:UNUSED_PAD src0_sel:DWORD
	s_nop 0
	v_or3_b32 v132, v34, v35, v133
	v_div_scale_f32 v34, s[0:1], v0, v0, 1.0
	v_rcp_f32_e32 v35, v34
	s_nop 0
	v_fma_f32 v36, -v34, v35, 1.0
	v_fmac_f32_e32 v35, v36, v35
	v_div_scale_f32 v36, vcc, 1.0, v0, 1.0
	v_mul_f32_e32 v37, v36, v35
	v_fma_f32 v38, -v34, v37, v36
	v_fmac_f32_e32 v37, v38, v35
	v_fma_f32 v34, -v34, v37, v36
	v_div_fmas_f32 v34, v34, v35, v37
	v_div_fixup_f32 v0, v34, v0, 1.0
	v_fma_f32 v0, v0, s80, 0.5
	v_cvt_u32_f32_e32 v134, v0
	v_mul_f32_e32 v0, 0xbfb8aa3b, v43
	v_exp_f32_e32 v0, v0
	s_nop 0
	v_add_f32_e32 v0, 1.0, v0
	v_div_scale_f32 v34, s[0:1], v0, v0, 1.0
	v_rcp_f32_e32 v35, v34
	s_nop 0
	v_fma_f32 v36, -v34, v35, 1.0
	v_fmac_f32_e32 v35, v36, v35
	v_div_scale_f32 v36, vcc, 1.0, v0, 1.0
	v_mul_f32_e32 v37, v36, v35
	v_fma_f32 v38, -v34, v37, v36
	v_fmac_f32_e32 v37, v38, v35
	v_fma_f32 v34, -v34, v37, v36
	v_div_fmas_f32 v34, v34, v35, v37
	v_div_fixup_f32 v0, v34, v0, 1.0
	v_mul_f32_e32 v34, 0xbfb8aa3b, v44
	v_exp_f32_e32 v34, v34
	v_fma_f32 v0, v0, s80, 0.5
	v_cvt_u32_f32_e32 v0, v0
	v_add_f32_e32 v34, 1.0, v34
	v_div_scale_f32 v35, s[0:1], v34, v34, 1.0
	v_rcp_f32_e32 v36, v35
	v_lshl_or_b32 v136, v0, 8, v134
	v_mul_f32_e32 v0, 0xbfb8aa3b, v46
	v_exp_f32_e32 v0, v0
	v_fma_f32 v37, -v35, v36, 1.0
	v_fmac_f32_e32 v36, v37, v36
	v_div_scale_f32 v37, vcc, 1.0, v34, 1.0
	v_mul_f32_e32 v38, v37, v36
	v_fma_f32 v39, -v35, v38, v37
	v_fmac_f32_e32 v38, v39, v36
	v_fma_f32 v35, -v35, v38, v37
	v_div_fmas_f32 v35, v35, v36, v38
	v_div_fixup_f32 v34, v35, v34, 1.0
	v_mul_f32_e32 v35, 0xbfb8aa3b, v45
	v_exp_f32_e32 v35, v35
	v_fma_f32 v34, v34, s80, 0.5
	v_cvt_u32_f32_sdwa v34, v34 dst_sel:WORD_1 dst_unused:UNUSED_PAD src0_sel:DWORD
	v_add_f32_e32 v0, 1.0, v0
	v_add_f32_e32 v35, 1.0, v35
	v_div_scale_f32 v36, s[0:1], v35, v35, 1.0
	v_rcp_f32_e32 v37, v36
	s_nop 0
	v_fma_f32 v38, -v36, v37, 1.0
	v_fmac_f32_e32 v37, v38, v37
	v_div_scale_f32 v38, vcc, 1.0, v35, 1.0
	v_mul_f32_e32 v39, v38, v37
	v_fma_f32 v40, -v36, v39, v38
	v_fmac_f32_e32 v39, v40, v37
	v_fma_f32 v36, -v36, v39, v38
	v_div_fmas_f32 v36, v36, v37, v39
	v_div_fixup_f32 v35, v36, v35, 1.0
	v_fma_f32 v35, v35, s80, 0.5
	v_cvt_u32_f32_sdwa v35, v35 dst_sel:BYTE_3 dst_unused:UNUSED_PAD src0_sel:DWORD
	s_nop 0
	v_or3_b32 v135, v34, v35, v136
	v_div_scale_f32 v34, s[0:1], v0, v0, 1.0
	v_rcp_f32_e32 v35, v34
	s_nop 0
	v_fma_f32 v36, -v34, v35, 1.0
	v_fmac_f32_e32 v35, v36, v35
	v_div_scale_f32 v36, vcc, 1.0, v0, 1.0
	v_mul_f32_e32 v37, v36, v35
	v_fma_f32 v38, -v34, v37, v36
	v_fmac_f32_e32 v37, v38, v35
	v_fma_f32 v34, -v34, v37, v36
	v_div_fmas_f32 v34, v34, v35, v37
	v_div_fixup_f32 v0, v34, v0, 1.0
	v_fma_f32 v0, v0, s80, 0.5
	v_cvt_u32_f32_e32 v137, v0
	v_mul_f32_e32 v0, 0xbfb8aa3b, v47
	v_exp_f32_e32 v0, v0
	s_nop 0
	v_add_f32_e32 v0, 1.0, v0
	v_div_scale_f32 v34, s[0:1], v0, v0, 1.0
	v_rcp_f32_e32 v35, v34
	s_nop 0
	v_fma_f32 v36, -v34, v35, 1.0
	v_fmac_f32_e32 v35, v36, v35
	v_div_scale_f32 v36, vcc, 1.0, v0, 1.0
	v_mul_f32_e32 v37, v36, v35
	v_fma_f32 v38, -v34, v37, v36
	v_fmac_f32_e32 v37, v38, v35
	v_fma_f32 v34, -v34, v37, v36
	v_div_fmas_f32 v34, v34, v35, v37
	v_div_fixup_f32 v0, v34, v0, 1.0
	v_mul_f32_e32 v34, 0xbfb8aa3b, v48
	v_exp_f32_e32 v34, v34
	v_fma_f32 v0, v0, s80, 0.5
	v_cvt_u32_f32_e32 v0, v0
	v_add_f32_e32 v34, 1.0, v34
	v_div_scale_f32 v35, s[0:1], v34, v34, 1.0
	v_rcp_f32_e32 v36, v35
	v_lshl_or_b32 v139, v0, 8, v137
	v_mul_f32_e32 v0, 0xbfb8aa3b, v18
	v_exp_f32_e32 v0, v0
	v_fma_f32 v37, -v35, v36, 1.0
	v_fmac_f32_e32 v36, v37, v36
	v_div_scale_f32 v37, vcc, 1.0, v34, 1.0
	v_mul_f32_e32 v38, v37, v36
	v_fma_f32 v39, -v35, v38, v37
	v_fmac_f32_e32 v38, v39, v36
	v_fma_f32 v35, -v35, v38, v37
	v_div_fmas_f32 v35, v35, v36, v38
	v_div_fixup_f32 v34, v35, v34, 1.0
	v_mul_f32_e32 v35, 0xbfb8aa3b, v49
	v_exp_f32_e32 v35, v35
	v_fma_f32 v34, v34, s80, 0.5
	v_cvt_u32_f32_sdwa v34, v34 dst_sel:WORD_1 dst_unused:UNUSED_PAD src0_sel:DWORD
	v_add_f32_e32 v0, 1.0, v0
	v_add_f32_e32 v35, 1.0, v35
	v_div_scale_f32 v36, s[0:1], v35, v35, 1.0
	v_rcp_f32_e32 v37, v36
	v_div_scale_f32 v18, s[0:1], v0, v0, 1.0
	v_fma_f32 v38, -v36, v37, 1.0
	v_fmac_f32_e32 v37, v38, v37
	v_div_scale_f32 v38, vcc, 1.0, v35, 1.0
	v_mul_f32_e32 v39, v38, v37
	v_fma_f32 v40, -v36, v39, v38
	v_fmac_f32_e32 v39, v40, v37
	v_fma_f32 v36, -v36, v39, v38
	v_div_fmas_f32 v36, v36, v37, v39
	v_div_fixup_f32 v35, v36, v35, 1.0
	v_fma_f32 v35, v35, s80, 0.5
	v_cvt_u32_f32_sdwa v35, v35 dst_sel:BYTE_3 dst_unused:UNUSED_PAD src0_sel:DWORD
	s_nop 0
	v_or3_b32 v138, v34, v35, v139
	v_rcp_f32_e32 v34, v18
	s_nop 0
	v_fma_f32 v35, -v18, v34, 1.0
	v_fmac_f32_e32 v34, v35, v34
	v_div_scale_f32 v35, vcc, 1.0, v0, 1.0
	v_mul_f32_e32 v36, v35, v34
	v_fma_f32 v37, -v18, v36, v35
	v_fmac_f32_e32 v36, v37, v34
	v_fma_f32 v18, -v18, v36, v35
	v_div_fmas_f32 v18, v18, v34, v36
	v_div_fixup_f32 v0, v18, v0, 1.0
	v_fma_f32 v0, v0, s80, 0.5
	v_cvt_u32_f32_e32 v140, v0
	v_mul_f32_e32 v0, 0xbfb8aa3b, v19
	v_exp_f32_e32 v0, v0
	s_nop 0
	v_add_f32_e32 v0, 1.0, v0
	v_div_scale_f32 v18, s[0:1], v0, v0, 1.0
	v_rcp_f32_e32 v19, v18
	s_nop 0
	v_fma_f32 v34, -v18, v19, 1.0
	v_fmac_f32_e32 v19, v34, v19
	v_div_scale_f32 v34, vcc, 1.0, v0, 1.0
	v_mul_f32_e32 v35, v34, v19
	v_fma_f32 v36, -v18, v35, v34
	v_fmac_f32_e32 v35, v36, v19
	v_fma_f32 v18, -v18, v35, v34
	v_div_fmas_f32 v18, v18, v19, v35
	v_div_fixup_f32 v0, v18, v0, 1.0
	v_mul_f32_e32 v18, 0xbfb8aa3b, v20
	v_exp_f32_e32 v18, v18
	v_fma_f32 v0, v0, s80, 0.5
	v_cvt_u32_f32_e32 v0, v0
	v_add_f32_e32 v18, 1.0, v18
	v_div_scale_f32 v19, s[0:1], v18, v18, 1.0
	v_rcp_f32_e32 v20, v19
	v_lshl_or_b32 v142, v0, 8, v140
	v_mul_f32_e32 v0, 0xbfb8aa3b, v22
	v_exp_f32_e32 v0, v0
	v_fma_f32 v34, -v19, v20, 1.0
	v_fmac_f32_e32 v20, v34, v20
	v_div_scale_f32 v34, vcc, 1.0, v18, 1.0
	v_mul_f32_e32 v35, v34, v20
	v_fma_f32 v36, -v19, v35, v34
	v_fmac_f32_e32 v35, v36, v20
	v_fma_f32 v19, -v19, v35, v34
	v_div_fmas_f32 v19, v19, v20, v35
	v_div_fixup_f32 v18, v19, v18, 1.0
	v_mul_f32_e32 v19, 0xbfb8aa3b, v21
	v_exp_f32_e32 v19, v19
	v_fma_f32 v18, v18, s80, 0.5
	v_cvt_u32_f32_sdwa v18, v18 dst_sel:WORD_1 dst_unused:UNUSED_PAD src0_sel:DWORD
	v_add_f32_e32 v0, 1.0, v0
	v_add_f32_e32 v19, 1.0, v19
	v_div_scale_f32 v20, s[0:1], v19, v19, 1.0
	v_rcp_f32_e32 v21, v20
	s_nop 0
	v_fma_f32 v34, -v20, v21, 1.0
	v_fmac_f32_e32 v21, v34, v21
	v_div_scale_f32 v34, vcc, 1.0, v19, 1.0
	v_mul_f32_e32 v35, v34, v21
	v_fma_f32 v36, -v20, v35, v34
	v_fmac_f32_e32 v35, v36, v21
	v_fma_f32 v20, -v20, v35, v34
	v_div_fmas_f32 v20, v20, v21, v35
	v_div_fixup_f32 v19, v20, v19, 1.0
	v_fma_f32 v19, v19, s80, 0.5
	v_cvt_u32_f32_sdwa v19, v19 dst_sel:BYTE_3 dst_unused:UNUSED_PAD src0_sel:DWORD
	s_nop 0
	v_or3_b32 v141, v18, v19, v142
	v_div_scale_f32 v18, s[0:1], v0, v0, 1.0
	v_rcp_f32_e32 v19, v18
	s_nop 0
	v_fma_f32 v20, -v18, v19, 1.0
	v_fmac_f32_e32 v19, v20, v19
	v_div_scale_f32 v20, vcc, 1.0, v0, 1.0
	v_mul_f32_e32 v21, v20, v19
	v_fma_f32 v22, -v18, v21, v20
	v_fmac_f32_e32 v21, v22, v19
	v_fma_f32 v18, -v18, v21, v20
	v_div_fmas_f32 v18, v18, v19, v21
	v_div_fixup_f32 v0, v18, v0, 1.0
	v_fma_f32 v0, v0, s80, 0.5
	v_cvt_u32_f32_e32 v143, v0
	v_mul_f32_e32 v0, 0xbfb8aa3b, v23
	v_exp_f32_e32 v0, v0
	s_nop 0
	v_add_f32_e32 v0, 1.0, v0
	v_div_scale_f32 v18, s[0:1], v0, v0, 1.0
	v_rcp_f32_e32 v19, v18
	s_nop 0
	v_fma_f32 v20, -v18, v19, 1.0
	v_fmac_f32_e32 v19, v20, v19
	v_div_scale_f32 v20, vcc, 1.0, v0, 1.0
	v_mul_f32_e32 v21, v20, v19
	v_fma_f32 v22, -v18, v21, v20
	v_fmac_f32_e32 v21, v22, v19
	v_fma_f32 v18, -v18, v21, v20
	v_div_fmas_f32 v18, v18, v19, v21
	v_div_fixup_f32 v0, v18, v0, 1.0
	v_mul_f32_e32 v18, 0xbfb8aa3b, v24
	v_exp_f32_e32 v18, v18
	v_fma_f32 v0, v0, s80, 0.5
	v_cvt_u32_f32_e32 v0, v0
	v_add_f32_e32 v18, 1.0, v18
	v_div_scale_f32 v19, s[0:1], v18, v18, 1.0
	v_rcp_f32_e32 v20, v19
	v_lshl_or_b32 v145, v0, 8, v143
	v_mul_f32_e32 v0, 0xbfb8aa3b, v26
	v_exp_f32_e32 v0, v0
	v_fma_f32 v21, -v19, v20, 1.0
	v_fmac_f32_e32 v20, v21, v20
	v_div_scale_f32 v21, vcc, 1.0, v18, 1.0
	v_mul_f32_e32 v22, v21, v20
	v_fma_f32 v23, -v19, v22, v21
	v_fmac_f32_e32 v22, v23, v20
	v_fma_f32 v19, -v19, v22, v21
	v_div_fmas_f32 v19, v19, v20, v22
	v_div_fixup_f32 v18, v19, v18, 1.0
	v_mul_f32_e32 v19, 0xbfb8aa3b, v25
	v_exp_f32_e32 v19, v19
	v_fma_f32 v18, v18, s80, 0.5
	v_cvt_u32_f32_sdwa v18, v18 dst_sel:WORD_1 dst_unused:UNUSED_PAD src0_sel:DWORD
	v_add_f32_e32 v0, 1.0, v0
	v_add_f32_e32 v19, 1.0, v19
	v_div_scale_f32 v20, s[0:1], v19, v19, 1.0
	v_rcp_f32_e32 v21, v20
	s_nop 0
	v_fma_f32 v22, -v20, v21, 1.0
	v_fmac_f32_e32 v21, v22, v21
	v_div_scale_f32 v22, vcc, 1.0, v19, 1.0
	v_mul_f32_e32 v23, v22, v21
	v_fma_f32 v24, -v20, v23, v22
	v_fmac_f32_e32 v23, v24, v21
	v_fma_f32 v20, -v20, v23, v22
	v_div_fmas_f32 v20, v20, v21, v23
	v_div_fixup_f32 v19, v20, v19, 1.0
	v_fma_f32 v19, v19, s80, 0.5
	v_cvt_u32_f32_sdwa v19, v19 dst_sel:BYTE_3 dst_unused:UNUSED_PAD src0_sel:DWORD
	s_nop 0
	v_or3_b32 v144, v18, v19, v145
	v_div_scale_f32 v18, s[0:1], v0, v0, 1.0
	v_rcp_f32_e32 v19, v18
	s_nop 0
	v_fma_f32 v20, -v18, v19, 1.0
	v_fmac_f32_e32 v19, v20, v19
	v_div_scale_f32 v20, vcc, 1.0, v0, 1.0
	v_mul_f32_e32 v21, v20, v19
	v_fma_f32 v22, -v18, v21, v20
	v_fmac_f32_e32 v21, v22, v19
	v_fma_f32 v18, -v18, v21, v20
	v_div_fmas_f32 v18, v18, v19, v21
	v_div_fixup_f32 v0, v18, v0, 1.0
	v_fma_f32 v0, v0, s80, 0.5
	v_cvt_u32_f32_e32 v146, v0
	v_mul_f32_e32 v0, 0xbfb8aa3b, v27
	v_exp_f32_e32 v0, v0
	s_nop 0
	v_add_f32_e32 v0, 1.0, v0
	v_div_scale_f32 v18, s[0:1], v0, v0, 1.0
	v_rcp_f32_e32 v19, v18
	s_nop 0
	v_fma_f32 v20, -v18, v19, 1.0
	v_fmac_f32_e32 v19, v20, v19
	v_div_scale_f32 v20, vcc, 1.0, v0, 1.0
	v_mul_f32_e32 v21, v20, v19
	v_fma_f32 v22, -v18, v21, v20
	v_fmac_f32_e32 v21, v22, v19
	v_fma_f32 v18, -v18, v21, v20
	v_div_fmas_f32 v18, v18, v19, v21
	v_div_fixup_f32 v0, v18, v0, 1.0
	v_mul_f32_e32 v18, 0xbfb8aa3b, v28
	v_exp_f32_e32 v18, v18
	v_fma_f32 v0, v0, s80, 0.5
	v_cvt_u32_f32_e32 v0, v0
	v_add_f32_e32 v18, 1.0, v18
	v_div_scale_f32 v19, s[0:1], v18, v18, 1.0
	v_rcp_f32_e32 v20, v19
	v_lshl_or_b32 v148, v0, 8, v146
	v_mul_f32_e32 v0, 0xbfb8aa3b, v30
	v_exp_f32_e32 v0, v0
	v_fma_f32 v21, -v19, v20, 1.0
	v_fmac_f32_e32 v20, v21, v20
	v_div_scale_f32 v21, vcc, 1.0, v18, 1.0
	v_mul_f32_e32 v22, v21, v20
	v_fma_f32 v23, -v19, v22, v21
	v_fmac_f32_e32 v22, v23, v20
	v_fma_f32 v19, -v19, v22, v21
	v_div_fmas_f32 v19, v19, v20, v22
	v_div_fixup_f32 v18, v19, v18, 1.0
	v_mul_f32_e32 v19, 0xbfb8aa3b, v29
	v_exp_f32_e32 v19, v19
	v_fma_f32 v18, v18, s80, 0.5
	v_cvt_u32_f32_sdwa v18, v18 dst_sel:WORD_1 dst_unused:UNUSED_PAD src0_sel:DWORD
	v_add_f32_e32 v0, 1.0, v0
	v_add_f32_e32 v19, 1.0, v19
	v_div_scale_f32 v20, s[0:1], v19, v19, 1.0
	v_rcp_f32_e32 v21, v20
	s_nop 0
	v_fma_f32 v22, -v20, v21, 1.0
	v_fmac_f32_e32 v21, v22, v21
	v_div_scale_f32 v22, vcc, 1.0, v19, 1.0
	v_mul_f32_e32 v23, v22, v21
	v_fma_f32 v24, -v20, v23, v22
	v_fmac_f32_e32 v23, v24, v21
	v_fma_f32 v20, -v20, v23, v22
	v_div_fmas_f32 v20, v20, v21, v23
	v_div_fixup_f32 v19, v20, v19, 1.0
	v_fma_f32 v19, v19, s80, 0.5
	v_cvt_u32_f32_sdwa v19, v19 dst_sel:BYTE_3 dst_unused:UNUSED_PAD src0_sel:DWORD
	s_nop 0
	v_or3_b32 v147, v18, v19, v148
	v_div_scale_f32 v18, s[0:1], v0, v0, 1.0
	v_rcp_f32_e32 v19, v18
	s_nop 0
	v_fma_f32 v20, -v18, v19, 1.0
	v_fmac_f32_e32 v19, v20, v19
	v_div_scale_f32 v20, vcc, 1.0, v0, 1.0
	v_mul_f32_e32 v21, v20, v19
	v_fma_f32 v22, -v18, v21, v20
	v_fmac_f32_e32 v21, v22, v19
	v_fma_f32 v18, -v18, v21, v20
	v_div_fmas_f32 v18, v18, v19, v21
	v_div_fixup_f32 v0, v18, v0, 1.0
	v_fma_f32 v0, v0, s80, 0.5
	v_cvt_u32_f32_e32 v149, v0
	v_mul_f32_e32 v0, 0xbfb8aa3b, v31
	v_exp_f32_e32 v0, v0
	s_nop 0
	v_add_f32_e32 v0, 1.0, v0
	v_div_scale_f32 v18, s[0:1], v0, v0, 1.0
	v_rcp_f32_e32 v19, v18
	s_nop 0
	v_fma_f32 v20, -v18, v19, 1.0
	v_fmac_f32_e32 v19, v20, v19
	v_div_scale_f32 v20, vcc, 1.0, v0, 1.0
	v_mul_f32_e32 v21, v20, v19
	v_fma_f32 v22, -v18, v21, v20
	v_fmac_f32_e32 v21, v22, v19
	v_fma_f32 v18, -v18, v21, v20
	v_div_fmas_f32 v18, v18, v19, v21
	v_div_fixup_f32 v0, v18, v0, 1.0
	v_mul_f32_e32 v18, 0xbfb8aa3b, v32
	v_exp_f32_e32 v18, v18
	v_fma_f32 v0, v0, s80, 0.5
	v_cvt_u32_f32_e32 v0, v0
	v_add_f32_e32 v18, 1.0, v18
	v_div_scale_f32 v19, s[0:1], v18, v18, 1.0
	v_rcp_f32_e32 v20, v19
	v_lshl_or_b32 v151, v0, 8, v149
	v_mul_f32_e32 v0, 0xbfb8aa3b, v2
	v_exp_f32_e32 v0, v0
	v_fma_f32 v21, -v19, v20, 1.0
	v_fmac_f32_e32 v20, v21, v20
	v_div_scale_f32 v21, vcc, 1.0, v18, 1.0
	v_mul_f32_e32 v22, v21, v20
	v_fma_f32 v23, -v19, v22, v21
	v_fmac_f32_e32 v22, v23, v20
	v_fma_f32 v19, -v19, v22, v21
	v_div_fmas_f32 v19, v19, v20, v22
	v_div_fixup_f32 v18, v19, v18, 1.0
	v_mul_f32_e32 v19, 0xbfb8aa3b, v33
	v_exp_f32_e32 v19, v19
	v_fma_f32 v18, v18, s80, 0.5
	v_cvt_u32_f32_sdwa v18, v18 dst_sel:WORD_1 dst_unused:UNUSED_PAD src0_sel:DWORD
	v_add_f32_e32 v0, 1.0, v0
	v_add_f32_e32 v19, 1.0, v19
	v_div_scale_f32 v20, s[0:1], v19, v19, 1.0
	v_rcp_f32_e32 v21, v20
	v_div_scale_f32 v2, s[0:1], v0, v0, 1.0
	v_fma_f32 v22, -v20, v21, 1.0
	v_fmac_f32_e32 v21, v22, v21
	v_div_scale_f32 v22, vcc, 1.0, v19, 1.0
	v_mul_f32_e32 v23, v22, v21
	v_fma_f32 v24, -v20, v23, v22
	v_fmac_f32_e32 v23, v24, v21
	v_fma_f32 v20, -v20, v23, v22
	v_div_fmas_f32 v20, v20, v21, v23
	v_div_fixup_f32 v19, v20, v19, 1.0
	v_fma_f32 v19, v19, s80, 0.5
	v_cvt_u32_f32_sdwa v19, v19 dst_sel:BYTE_3 dst_unused:UNUSED_PAD src0_sel:DWORD
	s_nop 0
	v_or3_b32 v150, v18, v19, v151
	v_rcp_f32_e32 v18, v2
	s_nop 0
	v_fma_f32 v19, -v2, v18, 1.0
	v_fmac_f32_e32 v18, v19, v18
	v_div_scale_f32 v19, vcc, 1.0, v0, 1.0
	v_mul_f32_e32 v20, v19, v18
	v_fma_f32 v21, -v2, v20, v19
	v_fmac_f32_e32 v20, v21, v18
	v_fma_f32 v2, -v2, v20, v19
	v_div_fmas_f32 v2, v2, v18, v20
	v_div_fixup_f32 v0, v2, v0, 1.0
	v_fma_f32 v0, v0, s80, 0.5
	v_cvt_u32_f32_e32 v152, v0
	v_mul_f32_e32 v0, 0xbfb8aa3b, v3
	v_exp_f32_e32 v0, v0
	s_nop 0
	v_add_f32_e32 v0, 1.0, v0
	v_div_scale_f32 v2, s[0:1], v0, v0, 1.0
	v_rcp_f32_e32 v3, v2
	s_nop 0
	v_fma_f32 v18, -v2, v3, 1.0
	v_fmac_f32_e32 v3, v18, v3
	v_div_scale_f32 v18, vcc, 1.0, v0, 1.0
	v_mul_f32_e32 v19, v18, v3
	v_fma_f32 v20, -v2, v19, v18
	v_fmac_f32_e32 v19, v20, v3
	v_fma_f32 v2, -v2, v19, v18
	v_div_fmas_f32 v2, v2, v3, v19
	v_div_fixup_f32 v0, v2, v0, 1.0
	v_mul_f32_e32 v2, 0xbfb8aa3b, v4
	v_exp_f32_e32 v2, v2
	v_fma_f32 v0, v0, s80, 0.5
	v_cvt_u32_f32_e32 v0, v0
	v_add_f32_e32 v2, 1.0, v2
	v_div_scale_f32 v3, s[0:1], v2, v2, 1.0
	v_rcp_f32_e32 v4, v3
	v_lshl_or_b32 v154, v0, 8, v152
	v_mul_f32_e32 v0, 0xbfb8aa3b, v6
	v_exp_f32_e32 v0, v0
	v_fma_f32 v18, -v3, v4, 1.0
	v_fmac_f32_e32 v4, v18, v4
	v_div_scale_f32 v18, vcc, 1.0, v2, 1.0
	v_mul_f32_e32 v19, v18, v4
	v_fma_f32 v20, -v3, v19, v18
	v_fmac_f32_e32 v19, v20, v4
	v_fma_f32 v3, -v3, v19, v18
	v_div_fmas_f32 v3, v3, v4, v19
	v_div_fixup_f32 v2, v3, v2, 1.0
	v_mul_f32_e32 v3, 0xbfb8aa3b, v5
	v_exp_f32_e32 v3, v3
	v_fma_f32 v2, v2, s80, 0.5
	v_cvt_u32_f32_sdwa v2, v2 dst_sel:WORD_1 dst_unused:UNUSED_PAD src0_sel:DWORD
	v_add_f32_e32 v0, 1.0, v0
	v_add_f32_e32 v3, 1.0, v3
	v_div_scale_f32 v4, s[0:1], v3, v3, 1.0
	v_rcp_f32_e32 v5, v4
	s_nop 0
	v_fma_f32 v18, -v4, v5, 1.0
	v_fmac_f32_e32 v5, v18, v5
	v_div_scale_f32 v18, vcc, 1.0, v3, 1.0
	v_mul_f32_e32 v19, v18, v5
	v_fma_f32 v20, -v4, v19, v18
	v_fmac_f32_e32 v19, v20, v5
	v_fma_f32 v4, -v4, v19, v18
	v_div_fmas_f32 v4, v4, v5, v19
	v_div_fixup_f32 v3, v4, v3, 1.0
	v_fma_f32 v3, v3, s80, 0.5
	v_cvt_u32_f32_sdwa v3, v3 dst_sel:BYTE_3 dst_unused:UNUSED_PAD src0_sel:DWORD
	s_nop 0
	v_or3_b32 v153, v2, v3, v154
	v_div_scale_f32 v2, s[0:1], v0, v0, 1.0
	v_rcp_f32_e32 v3, v2
	s_nop 0
	v_fma_f32 v4, -v2, v3, 1.0
	v_fmac_f32_e32 v3, v4, v3
	v_div_scale_f32 v4, vcc, 1.0, v0, 1.0
	v_mul_f32_e32 v5, v4, v3
	v_fma_f32 v6, -v2, v5, v4
	v_fmac_f32_e32 v5, v6, v3
	v_fma_f32 v2, -v2, v5, v4
	v_div_fmas_f32 v2, v2, v3, v5
	v_div_fixup_f32 v0, v2, v0, 1.0
	v_fma_f32 v0, v0, s80, 0.5
	v_cvt_u32_f32_e32 v155, v0
	v_mul_f32_e32 v0, 0xbfb8aa3b, v7
	v_exp_f32_e32 v0, v0
	s_nop 0
	v_add_f32_e32 v0, 1.0, v0
	v_div_scale_f32 v2, s[0:1], v0, v0, 1.0
	v_rcp_f32_e32 v3, v2
	s_nop 0
	v_fma_f32 v4, -v2, v3, 1.0
	v_fmac_f32_e32 v3, v4, v3
	v_div_scale_f32 v4, vcc, 1.0, v0, 1.0
	v_mul_f32_e32 v5, v4, v3
	v_fma_f32 v6, -v2, v5, v4
	v_fmac_f32_e32 v5, v6, v3
	v_fma_f32 v2, -v2, v5, v4
	v_div_fmas_f32 v2, v2, v3, v5
	v_div_fixup_f32 v0, v2, v0, 1.0
	v_mul_f32_e32 v2, 0xbfb8aa3b, v8
	v_exp_f32_e32 v2, v2
	v_fma_f32 v0, v0, s80, 0.5
	v_cvt_u32_f32_e32 v0, v0
	v_add_f32_e32 v2, 1.0, v2
	v_div_scale_f32 v3, s[0:1], v2, v2, 1.0
	v_rcp_f32_e32 v4, v3
	v_lshl_or_b32 v157, v0, 8, v155
	v_mul_f32_e32 v0, 0xbfb8aa3b, v10
	v_exp_f32_e32 v0, v0
	v_fma_f32 v5, -v3, v4, 1.0
	v_fmac_f32_e32 v4, v5, v4
	v_div_scale_f32 v5, vcc, 1.0, v2, 1.0
	v_mul_f32_e32 v6, v5, v4
	v_fma_f32 v7, -v3, v6, v5
	v_fmac_f32_e32 v6, v7, v4
	v_fma_f32 v3, -v3, v6, v5
	v_div_fmas_f32 v3, v3, v4, v6
	v_div_fixup_f32 v2, v3, v2, 1.0
	v_mul_f32_e32 v3, 0xbfb8aa3b, v9
	v_exp_f32_e32 v3, v3
	v_fma_f32 v2, v2, s80, 0.5
	v_cvt_u32_f32_sdwa v2, v2 dst_sel:WORD_1 dst_unused:UNUSED_PAD src0_sel:DWORD
	v_add_f32_e32 v0, 1.0, v0
	v_add_f32_e32 v3, 1.0, v3
	v_div_scale_f32 v4, s[0:1], v3, v3, 1.0
	v_rcp_f32_e32 v5, v4
	s_nop 0
	v_fma_f32 v6, -v4, v5, 1.0
	v_fmac_f32_e32 v5, v6, v5
	v_div_scale_f32 v6, vcc, 1.0, v3, 1.0
	v_mul_f32_e32 v7, v6, v5
	v_fma_f32 v8, -v4, v7, v6
	v_fmac_f32_e32 v7, v8, v5
	v_fma_f32 v4, -v4, v7, v6
	v_div_fmas_f32 v4, v4, v5, v7
	v_div_fixup_f32 v3, v4, v3, 1.0
	v_fma_f32 v3, v3, s80, 0.5
	v_cvt_u32_f32_sdwa v3, v3 dst_sel:BYTE_3 dst_unused:UNUSED_PAD src0_sel:DWORD
	s_nop 0
	v_or3_b32 v156, v2, v3, v157
	v_div_scale_f32 v2, s[0:1], v0, v0, 1.0
	v_rcp_f32_e32 v3, v2
	s_nop 0
	v_fma_f32 v4, -v2, v3, 1.0
	v_fmac_f32_e32 v3, v4, v3
	v_div_scale_f32 v4, vcc, 1.0, v0, 1.0
	v_mul_f32_e32 v5, v4, v3
	v_fma_f32 v6, -v2, v5, v4
	v_fmac_f32_e32 v5, v6, v3
	v_fma_f32 v2, -v2, v5, v4
	v_div_fmas_f32 v2, v2, v3, v5
	v_div_fixup_f32 v0, v2, v0, 1.0
	v_fma_f32 v0, v0, s80, 0.5
	v_cvt_u32_f32_e32 v158, v0
	v_mul_f32_e32 v0, 0xbfb8aa3b, v11
	v_exp_f32_e32 v0, v0
	s_nop 0
	v_add_f32_e32 v0, 1.0, v0
	v_div_scale_f32 v2, s[0:1], v0, v0, 1.0
	v_rcp_f32_e32 v3, v2
	s_nop 0
	v_fma_f32 v4, -v2, v3, 1.0
	v_fmac_f32_e32 v3, v4, v3
	v_div_scale_f32 v4, vcc, 1.0, v0, 1.0
	v_mul_f32_e32 v5, v4, v3
	v_fma_f32 v6, -v2, v5, v4
	v_fmac_f32_e32 v5, v6, v3
	v_fma_f32 v2, -v2, v5, v4
	v_div_fmas_f32 v2, v2, v3, v5
	v_div_fixup_f32 v0, v2, v0, 1.0
	v_mul_f32_e32 v2, 0xbfb8aa3b, v12
	v_exp_f32_e32 v2, v2
	v_fma_f32 v0, v0, s80, 0.5
	v_cvt_u32_f32_e32 v0, v0
	v_add_f32_e32 v2, 1.0, v2
	v_div_scale_f32 v3, s[0:1], v2, v2, 1.0
	v_rcp_f32_e32 v4, v3
	v_lshl_or_b32 v160, v0, 8, v158
	v_mul_f32_e32 v0, 0xbfb8aa3b, v14
	v_exp_f32_e32 v0, v0
	v_fma_f32 v5, -v3, v4, 1.0
	v_fmac_f32_e32 v4, v5, v4
	v_div_scale_f32 v5, vcc, 1.0, v2, 1.0
	v_mul_f32_e32 v6, v5, v4
	v_fma_f32 v7, -v3, v6, v5
	v_fmac_f32_e32 v6, v7, v4
	v_fma_f32 v3, -v3, v6, v5
	v_div_fmas_f32 v3, v3, v4, v6
	v_div_fixup_f32 v2, v3, v2, 1.0
	v_mul_f32_e32 v3, 0xbfb8aa3b, v13
	v_exp_f32_e32 v3, v3
	v_fma_f32 v2, v2, s80, 0.5
	v_cvt_u32_f32_sdwa v2, v2 dst_sel:WORD_1 dst_unused:UNUSED_PAD src0_sel:DWORD
	v_add_f32_e32 v0, 1.0, v0
	v_add_f32_e32 v3, 1.0, v3
	v_div_scale_f32 v4, s[0:1], v3, v3, 1.0
	v_rcp_f32_e32 v5, v4
	s_nop 0
	v_fma_f32 v6, -v4, v5, 1.0
	v_fmac_f32_e32 v5, v6, v5
	v_div_scale_f32 v6, vcc, 1.0, v3, 1.0
	v_mul_f32_e32 v7, v6, v5
	v_fma_f32 v8, -v4, v7, v6
	v_fmac_f32_e32 v7, v8, v5
	v_fma_f32 v4, -v4, v7, v6
	v_div_fmas_f32 v4, v4, v5, v7
	v_div_fixup_f32 v3, v4, v3, 1.0
	v_fma_f32 v3, v3, s80, 0.5
	v_cvt_u32_f32_sdwa v3, v3 dst_sel:BYTE_3 dst_unused:UNUSED_PAD src0_sel:DWORD
	s_nop 0
	v_or3_b32 v159, v2, v3, v160
	v_div_scale_f32 v2, s[0:1], v0, v0, 1.0
	v_rcp_f32_e32 v3, v2
	s_nop 0
	v_fma_f32 v4, -v2, v3, 1.0
	v_fmac_f32_e32 v3, v4, v3
	v_div_scale_f32 v4, vcc, 1.0, v0, 1.0
	v_mul_f32_e32 v5, v4, v3
	v_fma_f32 v6, -v2, v5, v4
	v_fmac_f32_e32 v5, v6, v3
	v_fma_f32 v2, -v2, v5, v4
	v_div_fmas_f32 v2, v2, v3, v5
	v_div_fixup_f32 v0, v2, v0, 1.0
	v_fma_f32 v0, v0, s80, 0.5
	v_cvt_u32_f32_e32 v161, v0
	v_mul_f32_e32 v0, 0xbfb8aa3b, v15
	v_exp_f32_e32 v0, v0
	s_nop 0
	v_add_f32_e32 v0, 1.0, v0
	v_div_scale_f32 v2, s[0:1], v0, v0, 1.0
	v_rcp_f32_e32 v3, v2
	s_nop 0
	v_fma_f32 v4, -v2, v3, 1.0
	v_fmac_f32_e32 v3, v4, v3
	v_div_scale_f32 v4, vcc, 1.0, v0, 1.0
	v_mul_f32_e32 v5, v4, v3
	v_fma_f32 v6, -v2, v5, v4
	v_fmac_f32_e32 v5, v6, v3
	v_fma_f32 v2, -v2, v5, v4
	v_div_fmas_f32 v2, v2, v3, v5
	v_div_fixup_f32 v0, v2, v0, 1.0
	v_mul_f32_e32 v2, 0xbfb8aa3b, v16
	v_exp_f32_e32 v2, v2
	v_fma_f32 v0, v0, s80, 0.5
	v_cvt_u32_f32_e32 v0, v0
	v_add_f32_e32 v2, 1.0, v2
	v_div_scale_f32 v3, s[0:1], v2, v2, 1.0
	v_rcp_f32_e32 v4, v3
	v_lshl_or_b32 v163, v0, 8, v161
	v_fma_f32 v5, -v3, v4, 1.0
	v_fmac_f32_e32 v4, v5, v4
	v_div_scale_f32 v5, vcc, 1.0, v2, 1.0
	v_mul_f32_e32 v6, v5, v4
	v_fma_f32 v7, -v3, v6, v5
	v_fmac_f32_e32 v6, v7, v4
	v_fma_f32 v3, -v3, v6, v5
	v_div_fmas_f32 v3, v3, v4, v6
	v_div_fixup_f32 v2, v3, v2, 1.0
	v_mul_f32_e32 v3, 0xbfb8aa3b, v17
	v_exp_f32_e32 v3, v3
	v_fma_f32 v2, v2, s80, 0.5
	v_cvt_u32_f32_sdwa v2, v2 dst_sel:WORD_1 dst_unused:UNUSED_PAD src0_sel:DWORD
	v_add_f32_e32 v3, 1.0, v3
	v_div_scale_f32 v4, s[0:1], v3, v3, 1.0
	v_rcp_f32_e32 v5, v4
	s_movk_i32 s0, 0xaa0
	s_cselect_b32 s12, s0, 0x12a0
	s_mov_b32 s0, 0x12f0000
	v_fma_f32 v6, -v4, v5, 1.0
	v_fmac_f32_e32 v5, v6, v5
	v_div_scale_f32 v6, vcc, 1.0, v3, 1.0
	v_mul_f32_e32 v7, v6, v5
	v_fma_f32 v8, -v4, v7, v6
	v_fmac_f32_e32 v7, v8, v5
	v_fma_f32 v4, -v4, v7, v6
	v_div_fmas_f32 v4, v4, v5, v7
	s_cselect_b32 s13, s0, 0x13f0000
	s_cmp_eq_u32 s45, 0
	v_div_fixup_f32 v3, v4, v3, 1.0
	s_cselect_b64 vcc, -1, 0
	v_fma_f32 v3, v3, s80, 0.5
	s_and_b64 s[0:1], vcc, exec
	v_cvt_u32_f32_sdwa v3, v3 dst_sel:BYTE_3 dst_unused:UNUSED_PAD src0_sel:DWORD
	s_cselect_b32 s0, 0x2a0, s12
	s_cselect_b32 s13, 0x11f0000, s13
	s_lshl_b32 s0, s0, 1
	s_add_u32 s0, s43, s0
	v_mov_b32_e32 v6, v178
	s_addc_u32 s1, s44, 0
	v_or3_b32 v162, v2, v3, v163
	v_lshlrev_b32_e32 v0, 3, v6
	v_ashrrev_i32_e32 v2, 3, v6
	v_and_b32_e32 v36, 56, v0
	v_mov_b64_e32 v[4:5], s[0:1]
	s_add_u32 s12, s25, s13
	v_ashrrev_i32_e32 v3, 31, v2
	v_mad_i64_i32 v[4:5], s[0:1], v2, s77, v[4:5]
	v_lshlrev_b32_e32 v0, 1, v36
	s_addc_u32 s13, s42, 0
	v_lshl_add_u64 v[102:103], v[4:5], 0, v[0:1]
	v_lshlrev_b64 v[4:5], 10, v[2:3]
	v_lshl_add_u64 v[4:5], s[12:13], 0, v[4:5]
	v_and_b32_e32 v7, 31, v6
	v_lshl_add_u64 v[100:101], v[4:5], 0, v[0:1]
	v_lshrrev_b32_e32 v0, 1, v6
	v_and_or_b32 v3, v0, s35, v7
	v_and_b32_e32 v0, 16, v0
	v_mad_u64_u32 v[98:99], s[0:1], v3, s72, v[0:1]
	v_and_b32_e32 v0, 7, v178
	v_bfe_u32 v98, v178, 4, 3
	v_xor_b32_e32 v98, v98, v0
	v_sub_u32_e32 v98, v98, v0
	v_lshlrev_b32_e32 v98, 4, v98
	v_ashrrev_i32_e32 v99, 31, v98
	v_lshl_add_u64 v[102:103], v[102:103], 0, v[98:99]
	v_lshl_add_u64 v[100:101], v[100:101], 0, v[98:99]
	s_mov_b32 s15, 0x18000
	v_add_co_u32_e64 v104, s[0:1], s97, v102
	s_nop 1
	v_addc_co_u32_e64 v105, s[0:1], 0, v103, s[0:1]
	v_add_co_u32_e64 v106, s[0:1], s31, v100
	s_nop 1
	v_addc_co_u32_e64 v107, s[0:1], 0, v101, s[0:1]
	v_add_co_u32_e64 v108, s[0:1], s26, v102
	s_nop 1
	v_addc_co_u32_e64 v109, s[0:1], 0, v103, s[0:1]
	v_add_co_u32_e64 v110, s[0:1], s73, v100
	s_nop 1
	v_addc_co_u32_e64 v111, s[0:1], 0, v101, s[0:1]
	v_add_co_u32_e64 v112, s[0:1], s96, v102
	s_nop 1
	v_addc_co_u32_e64 v113, s[0:1], 0, v103, s[0:1]
	v_add_co_u32_e64 v114, s[0:1], s15, v100
	s_nop 1
	v_addc_co_u32_e64 v115, s[0:1], 0, v101, s[0:1]
	v_and_b32_e32 v0, 31, v178
	v_bfe_u32 v98, v178, 5, 1
	v_bfe_u32 v99, v178, 1, 3
	v_xor_b32_e32 v98, v98, v99
	v_lshlrev_b32_e32 v98, 4, v98
	v_lshl_add_u32 v98, v0, 7, v98
	v_bfe_u32 v99, v178, 7, 1
	v_lshl_add_u32 v222, v99, 13, v98
	v_bfe_u32 v99, v178, 6, 1
	v_lshl_add_u32 v226, v99, 13, v98
	v_add_u32_e32 v226, 0x4000, v226
	v_xor_b32_e32 v223, 32, v222
	v_xor_b32_e32 v227, 32, v226
	v_xor_b32_e32 v224, 64, v222
	v_xor_b32_e32 v228, 64, v226
	v_xor_b32_e32 v225, 96, v222
	v_xor_b32_e32 v229, 96, v226
	v_lshrrev_b32_e32 v98, 6, v178
	v_lshlrev_b32_e32 v98, 10, v98
	s_nop 1
	v_readfirstlane_b32 s14, v98
	s_add_u32 m0, s14, 0x800
	s_nop 0
	global_load_lds_dwordx4 v[102:103], off
	s_add_u32 m0, s14, 0x1800
	s_nop 0
	global_load_lds_dwordx4 v[104:105], off
	s_add_u32 m0, s14, 0x2800
	s_nop 0
	global_load_lds_dwordx4 v[108:109], off
	s_add_u32 m0, s14, 0x3800
	s_nop 0
	global_load_lds_dwordx4 v[112:113], off
	s_add_u32 m0, s14, 0x4800
	s_nop 0
	global_load_lds_dwordx4 v[100:101], off
	s_add_u32 m0, s14, 0x5800
	s_nop 0
	global_load_lds_dwordx4 v[106:107], off
	s_add_u32 m0, s14, 0x6800
	s_nop 0
	global_load_lds_dwordx4 v[110:111], off
	s_add_u32 m0, s14, 0x7800
	s_nop 0
	global_load_lds_dwordx4 v[114:115], off
	s_add_u32 m0, s14, 0x8780
	s_nop 0
	global_load_lds_dwordx4 v[102:103], off offset:128
	s_add_u32 m0, s14, 0x9780
	s_nop 0
	global_load_lds_dwordx4 v[104:105], off offset:128
	s_add_u32 m0, s14, 0xa780
	s_nop 0
	global_load_lds_dwordx4 v[108:109], off offset:128
	s_add_u32 m0, s14, 0xb780
	s_nop 0
	global_load_lds_dwordx4 v[112:113], off offset:128
	s_add_u32 m0, s14, 0xc780
	s_nop 0
	global_load_lds_dwordx4 v[100:101], off offset:128
	s_add_u32 m0, s14, 0xd780
	s_nop 0
	global_load_lds_dwordx4 v[106:107], off offset:128
	s_add_u32 m0, s14, 0xe780
	s_nop 0
	global_load_lds_dwordx4 v[110:111], off offset:128
	s_add_u32 m0, s14, 0xf780
	s_nop 0
	global_load_lds_dwordx4 v[114:115], off offset:128
	s_waitcnt vmcnt(8)
	s_barrier
	ds_read_b128 v[66:69], v222 offset:2048
	ds_read_b128 v[70:73], v222 offset:6144
	ds_read_b128 v[74:77], v226 offset:2048
	ds_read_b128 v[78:81], v226 offset:6144
	ds_read_b128 v[82:85], v223 offset:2048
	ds_read_b128 v[86:89], v223 offset:6144
	ds_read_b128 v[90:93], v227 offset:2048
	ds_read_b128 v[94:97], v227 offset:6144
	ds_read_b128 v[230:233], v224 offset:2048
	ds_read_b128 v[234:237], v224 offset:6144
	ds_read_b128 v[238:241], v228 offset:2048
	ds_read_b128 v[242:245], v228 offset:6144
	s_waitcnt lgkmcnt(8)
	v_mfma_f32_32x32x16_bf16 v[2:17], v[66:69], v[74:77], 0
	v_mfma_f32_32x32x16_bf16 v[50:65], v[66:69], v[78:81], 0
	v_mfma_f32_32x32x16_bf16 v[34:49], v[70:73], v[74:77], 0
	v_mfma_f32_32x32x16_bf16 v[18:33], v[70:73], v[78:81], 0
	ds_read_b128 v[66:69], v225 offset:2048
	ds_read_b128 v[70:73], v225 offset:6144
	ds_read_b128 v[74:77], v229 offset:2048
	ds_read_b128 v[78:81], v229 offset:6144
	s_waitcnt lgkmcnt(8)
	v_mfma_f32_32x32x16_bf16 v[2:17], v[82:85], v[90:93], v[2:17]
	v_mfma_f32_32x32x16_bf16 v[50:65], v[82:85], v[94:97], v[50:65]
	v_mfma_f32_32x32x16_bf16 v[34:49], v[86:89], v[90:93], v[34:49]
	v_mfma_f32_32x32x16_bf16 v[18:33], v[86:89], v[94:97], v[18:33]
	s_waitcnt lgkmcnt(0)
	s_barrier
	s_add_u32 m0, s14, 0x700
	s_nop 0
	global_load_lds_dwordx4 v[102:103], off offset:256
	s_add_u32 m0, s14, 0x1700
	s_nop 0
	global_load_lds_dwordx4 v[104:105], off offset:256
	s_add_u32 m0, s14, 0x2700
	s_nop 0
	global_load_lds_dwordx4 v[108:109], off offset:256
	s_add_u32 m0, s14, 0x3700
	s_nop 0
	global_load_lds_dwordx4 v[112:113], off offset:256
	s_add_u32 m0, s14, 0x4700
	s_nop 0
	global_load_lds_dwordx4 v[100:101], off offset:256
	s_add_u32 m0, s14, 0x5700
	s_nop 0
	global_load_lds_dwordx4 v[106:107], off offset:256
	s_add_u32 m0, s14, 0x6700
	s_nop 0
	global_load_lds_dwordx4 v[110:111], off offset:256
	s_add_u32 m0, s14, 0x7700
	s_nop 0
	global_load_lds_dwordx4 v[114:115], off offset:256
	s_waitcnt vmcnt(8)
	s_barrier
	ds_read_b128 v[82:85], v222 offset:34816
	ds_read_b128 v[86:89], v222 offset:38912
	ds_read_b128 v[90:93], v226 offset:34816
	ds_read_b128 v[94:97], v226 offset:38912
	v_mfma_f32_32x32x16_bf16 v[2:17], v[230:233], v[238:241], v[2:17]
	v_mfma_f32_32x32x16_bf16 v[50:65], v[230:233], v[242:245], v[50:65]
	v_mfma_f32_32x32x16_bf16 v[34:49], v[234:237], v[238:241], v[34:49]
	v_mfma_f32_32x32x16_bf16 v[18:33], v[234:237], v[242:245], v[18:33]
	ds_read_b128 v[230:233], v223 offset:34816
	ds_read_b128 v[234:237], v223 offset:38912
	ds_read_b128 v[238:241], v227 offset:34816
	ds_read_b128 v[242:245], v227 offset:38912
	v_mfma_f32_32x32x16_bf16 v[2:17], v[66:69], v[74:77], v[2:17]
	v_mfma_f32_32x32x16_bf16 v[50:65], v[66:69], v[78:81], v[50:65]
	v_mfma_f32_32x32x16_bf16 v[34:49], v[70:73], v[74:77], v[34:49]
	v_mfma_f32_32x32x16_bf16 v[18:33], v[70:73], v[78:81], v[18:33]
	ds_read_b128 v[66:69], v224 offset:34816
	ds_read_b128 v[70:73], v224 offset:38912
	ds_read_b128 v[74:77], v228 offset:34816
	ds_read_b128 v[78:81], v228 offset:38912
	s_waitcnt lgkmcnt(8)
	v_mfma_f32_32x32x16_bf16 v[2:17], v[82:85], v[90:93], v[2:17]
	v_mfma_f32_32x32x16_bf16 v[50:65], v[82:85], v[94:97], v[50:65]
	v_mfma_f32_32x32x16_bf16 v[34:49], v[86:89], v[90:93], v[34:49]
	v_mfma_f32_32x32x16_bf16 v[18:33], v[86:89], v[94:97], v[18:33]
	ds_read_b128 v[82:85], v225 offset:34816
	ds_read_b128 v[86:89], v225 offset:38912
	ds_read_b128 v[90:93], v229 offset:34816
	ds_read_b128 v[94:97], v229 offset:38912
	s_waitcnt lgkmcnt(8)
	v_mfma_f32_32x32x16_bf16 v[2:17], v[230:233], v[238:241], v[2:17]
	v_mfma_f32_32x32x16_bf16 v[50:65], v[230:233], v[242:245], v[50:65]
	v_mfma_f32_32x32x16_bf16 v[34:49], v[234:237], v[238:241], v[34:49]
	v_mfma_f32_32x32x16_bf16 v[18:33], v[234:237], v[242:245], v[18:33]
	s_waitcnt lgkmcnt(0)
	s_barrier
	s_add_u32 m0, s14, 0x8680
	s_nop 0
	global_load_lds_dwordx4 v[102:103], off offset:384
	s_add_u32 m0, s14, 0x9680
	s_nop 0
	global_load_lds_dwordx4 v[104:105], off offset:384
	s_add_u32 m0, s14, 0xa680
	s_nop 0
	global_load_lds_dwordx4 v[108:109], off offset:384
	s_add_u32 m0, s14, 0xb680
	s_nop 0
	global_load_lds_dwordx4 v[112:113], off offset:384
	s_add_u32 m0, s14, 0xc680
	s_nop 0
	global_load_lds_dwordx4 v[100:101], off offset:384
	s_add_u32 m0, s14, 0xd680
	s_nop 0
	global_load_lds_dwordx4 v[106:107], off offset:384
	s_add_u32 m0, s14, 0xe680
	s_nop 0
	global_load_lds_dwordx4 v[110:111], off offset:384
	s_add_u32 m0, s14, 0xf680
	s_nop 0
	global_load_lds_dwordx4 v[114:115], off offset:384
	s_waitcnt vmcnt(8)
	s_barrier
	ds_read_b128 v[230:233], v222 offset:2048
	ds_read_b128 v[234:237], v222 offset:6144
	ds_read_b128 v[238:241], v226 offset:2048
	ds_read_b128 v[242:245], v226 offset:6144
	v_mfma_f32_32x32x16_bf16 v[2:17], v[66:69], v[74:77], v[2:17]
	v_mfma_f32_32x32x16_bf16 v[50:65], v[66:69], v[78:81], v[50:65]
	v_mfma_f32_32x32x16_bf16 v[34:49], v[70:73], v[74:77], v[34:49]
	v_mfma_f32_32x32x16_bf16 v[18:33], v[70:73], v[78:81], v[18:33]
	ds_read_b128 v[66:69], v223 offset:2048
	ds_read_b128 v[70:73], v223 offset:6144
	ds_read_b128 v[74:77], v227 offset:2048
	ds_read_b128 v[78:81], v227 offset:6144
	v_mfma_f32_32x32x16_bf16 v[2:17], v[82:85], v[90:93], v[2:17]
	v_mfma_f32_32x32x16_bf16 v[50:65], v[82:85], v[94:97], v[50:65]
	v_mfma_f32_32x32x16_bf16 v[34:49], v[86:89], v[90:93], v[34:49]
	v_mfma_f32_32x32x16_bf16 v[18:33], v[86:89], v[94:97], v[18:33]
	ds_read_b128 v[82:85], v224 offset:2048
	ds_read_b128 v[86:89], v224 offset:6144
	ds_read_b128 v[90:93], v228 offset:2048
	ds_read_b128 v[94:97], v228 offset:6144
	s_waitcnt lgkmcnt(8)
	v_mfma_f32_32x32x16_bf16 v[2:17], v[230:233], v[238:241], v[2:17]
	v_mfma_f32_32x32x16_bf16 v[50:65], v[230:233], v[242:245], v[50:65]
	v_mfma_f32_32x32x16_bf16 v[34:49], v[234:237], v[238:241], v[34:49]
	v_mfma_f32_32x32x16_bf16 v[18:33], v[234:237], v[242:245], v[18:33]
	ds_read_b128 v[230:233], v225 offset:2048
	ds_read_b128 v[234:237], v225 offset:6144
	ds_read_b128 v[238:241], v229 offset:2048
	ds_read_b128 v[242:245], v229 offset:6144
	s_waitcnt lgkmcnt(8)
	v_mfma_f32_32x32x16_bf16 v[2:17], v[66:69], v[74:77], v[2:17]
	v_mfma_f32_32x32x16_bf16 v[50:65], v[66:69], v[78:81], v[50:65]
	v_mfma_f32_32x32x16_bf16 v[34:49], v[70:73], v[74:77], v[34:49]
	v_mfma_f32_32x32x16_bf16 v[18:33], v[70:73], v[78:81], v[18:33]
	s_waitcnt lgkmcnt(0)
	s_barrier
	s_add_u32 m0, s14, 0x600
	s_nop 0
	global_load_lds_dwordx4 v[102:103], off offset:512
	s_add_u32 m0, s14, 0x1600
	s_nop 0
	global_load_lds_dwordx4 v[104:105], off offset:512
	s_add_u32 m0, s14, 0x2600
	s_nop 0
	global_load_lds_dwordx4 v[108:109], off offset:512
	s_add_u32 m0, s14, 0x3600
	s_nop 0
	global_load_lds_dwordx4 v[112:113], off offset:512
	s_add_u32 m0, s14, 0x4600
	s_nop 0
	global_load_lds_dwordx4 v[100:101], off offset:512
	s_add_u32 m0, s14, 0x5600
	s_nop 0
	global_load_lds_dwordx4 v[106:107], off offset:512
	s_add_u32 m0, s14, 0x6600
	s_nop 0
	global_load_lds_dwordx4 v[110:111], off offset:512
	s_add_u32 m0, s14, 0x7600
	s_nop 0
	global_load_lds_dwordx4 v[114:115], off offset:512
	s_waitcnt vmcnt(8)
	s_barrier
	ds_read_b128 v[66:69], v222 offset:34816
	ds_read_b128 v[70:73], v222 offset:38912
	ds_read_b128 v[74:77], v226 offset:34816
	ds_read_b128 v[78:81], v226 offset:38912
	v_mfma_f32_32x32x16_bf16 v[2:17], v[82:85], v[90:93], v[2:17]
	v_mfma_f32_32x32x16_bf16 v[50:65], v[82:85], v[94:97], v[50:65]
	v_mfma_f32_32x32x16_bf16 v[34:49], v[86:89], v[90:93], v[34:49]
	v_mfma_f32_32x32x16_bf16 v[18:33], v[86:89], v[94:97], v[18:33]
	ds_read_b128 v[82:85], v223 offset:34816
	ds_read_b128 v[86:89], v223 offset:38912
	ds_read_b128 v[90:93], v227 offset:34816
	ds_read_b128 v[94:97], v227 offset:38912
	v_mfma_f32_32x32x16_bf16 v[2:17], v[230:233], v[238:241], v[2:17]
	v_mfma_f32_32x32x16_bf16 v[50:65], v[230:233], v[242:245], v[50:65]
	v_mfma_f32_32x32x16_bf16 v[34:49], v[234:237], v[238:241], v[34:49]
	v_mfma_f32_32x32x16_bf16 v[18:33], v[234:237], v[242:245], v[18:33]
	ds_read_b128 v[230:233], v224 offset:34816
	ds_read_b128 v[234:237], v224 offset:38912
	ds_read_b128 v[238:241], v228 offset:34816
	ds_read_b128 v[242:245], v228 offset:38912
	s_waitcnt lgkmcnt(8)
	v_mfma_f32_32x32x16_bf16 v[2:17], v[66:69], v[74:77], v[2:17]
	v_mfma_f32_32x32x16_bf16 v[50:65], v[66:69], v[78:81], v[50:65]
	v_mfma_f32_32x32x16_bf16 v[34:49], v[70:73], v[74:77], v[34:49]
	v_mfma_f32_32x32x16_bf16 v[18:33], v[70:73], v[78:81], v[18:33]
	ds_read_b128 v[66:69], v225 offset:34816
	ds_read_b128 v[70:73], v225 offset:38912
	ds_read_b128 v[74:77], v229 offset:34816
	ds_read_b128 v[78:81], v229 offset:38912
	s_waitcnt lgkmcnt(8)
	v_mfma_f32_32x32x16_bf16 v[2:17], v[82:85], v[90:93], v[2:17]
	v_mfma_f32_32x32x16_bf16 v[50:65], v[82:85], v[94:97], v[50:65]
	v_mfma_f32_32x32x16_bf16 v[34:49], v[86:89], v[90:93], v[34:49]
	v_mfma_f32_32x32x16_bf16 v[18:33], v[86:89], v[94:97], v[18:33]
	s_waitcnt lgkmcnt(0)
	s_barrier
	s_add_u32 m0, s14, 0x8580
	s_nop 0
	global_load_lds_dwordx4 v[102:103], off offset:640
	s_add_u32 m0, s14, 0x9580
	s_nop 0
	global_load_lds_dwordx4 v[104:105], off offset:640
	s_add_u32 m0, s14, 0xa580
	s_nop 0
	global_load_lds_dwordx4 v[108:109], off offset:640
	s_add_u32 m0, s14, 0xb580
	s_nop 0
	global_load_lds_dwordx4 v[112:113], off offset:640
	s_add_u32 m0, s14, 0xc580
	s_nop 0
	global_load_lds_dwordx4 v[100:101], off offset:640
	s_add_u32 m0, s14, 0xd580
	s_nop 0
	global_load_lds_dwordx4 v[106:107], off offset:640
	s_add_u32 m0, s14, 0xe580
	s_nop 0
	global_load_lds_dwordx4 v[110:111], off offset:640
	s_add_u32 m0, s14, 0xf580
	s_nop 0
	global_load_lds_dwordx4 v[114:115], off offset:640
	s_waitcnt vmcnt(8)
	s_barrier
	ds_read_b128 v[82:85], v222 offset:2048
	ds_read_b128 v[86:89], v222 offset:6144
	ds_read_b128 v[90:93], v226 offset:2048
	ds_read_b128 v[94:97], v226 offset:6144
	v_mfma_f32_32x32x16_bf16 v[2:17], v[230:233], v[238:241], v[2:17]
	v_mfma_f32_32x32x16_bf16 v[50:65], v[230:233], v[242:245], v[50:65]
	v_mfma_f32_32x32x16_bf16 v[34:49], v[234:237], v[238:241], v[34:49]
	v_mfma_f32_32x32x16_bf16 v[18:33], v[234:237], v[242:245], v[18:33]
	ds_read_b128 v[230:233], v223 offset:2048
	ds_read_b128 v[234:237], v223 offset:6144
	ds_read_b128 v[238:241], v227 offset:2048
	ds_read_b128 v[242:245], v227 offset:6144
	v_mfma_f32_32x32x16_bf16 v[2:17], v[66:69], v[74:77], v[2:17]
	v_mfma_f32_32x32x16_bf16 v[50:65], v[66:69], v[78:81], v[50:65]
	v_mfma_f32_32x32x16_bf16 v[34:49], v[70:73], v[74:77], v[34:49]
	v_mfma_f32_32x32x16_bf16 v[18:33], v[70:73], v[78:81], v[18:33]
	ds_read_b128 v[66:69], v224 offset:2048
	ds_read_b128 v[70:73], v224 offset:6144
	ds_read_b128 v[74:77], v228 offset:2048
	ds_read_b128 v[78:81], v228 offset:6144
	s_waitcnt lgkmcnt(8)
	v_mfma_f32_32x32x16_bf16 v[2:17], v[82:85], v[90:93], v[2:17]
	v_mfma_f32_32x32x16_bf16 v[50:65], v[82:85], v[94:97], v[50:65]
	v_mfma_f32_32x32x16_bf16 v[34:49], v[86:89], v[90:93], v[34:49]
	v_mfma_f32_32x32x16_bf16 v[18:33], v[86:89], v[94:97], v[18:33]
	ds_read_b128 v[82:85], v225 offset:2048
	ds_read_b128 v[86:89], v225 offset:6144
	ds_read_b128 v[90:93], v229 offset:2048
	ds_read_b128 v[94:97], v229 offset:6144
	s_waitcnt lgkmcnt(8)
	v_mfma_f32_32x32x16_bf16 v[2:17], v[230:233], v[238:241], v[2:17]
	v_mfma_f32_32x32x16_bf16 v[50:65], v[230:233], v[242:245], v[50:65]
	v_mfma_f32_32x32x16_bf16 v[34:49], v[234:237], v[238:241], v[34:49]
	v_mfma_f32_32x32x16_bf16 v[18:33], v[234:237], v[242:245], v[18:33]
	s_waitcnt lgkmcnt(0)
	s_barrier
	s_add_u32 m0, s14, 0x500
	s_nop 0
	global_load_lds_dwordx4 v[102:103], off offset:768
	s_add_u32 m0, s14, 0x1500
	s_nop 0
	global_load_lds_dwordx4 v[104:105], off offset:768
	s_add_u32 m0, s14, 0x2500
	s_nop 0
	global_load_lds_dwordx4 v[108:109], off offset:768
	s_add_u32 m0, s14, 0x3500
	s_nop 0
	global_load_lds_dwordx4 v[112:113], off offset:768
	s_add_u32 m0, s14, 0x4500
	s_nop 0
	global_load_lds_dwordx4 v[100:101], off offset:768
	s_add_u32 m0, s14, 0x5500
	s_nop 0
	global_load_lds_dwordx4 v[106:107], off offset:768
	s_add_u32 m0, s14, 0x6500
	s_nop 0
	global_load_lds_dwordx4 v[110:111], off offset:768
	s_add_u32 m0, s14, 0x7500
	s_nop 0
	global_load_lds_dwordx4 v[114:115], off offset:768
	s_waitcnt vmcnt(8)
	s_barrier
	ds_read_b128 v[230:233], v222 offset:34816
	ds_read_b128 v[234:237], v222 offset:38912
	ds_read_b128 v[238:241], v226 offset:34816
	ds_read_b128 v[242:245], v226 offset:38912
	v_mfma_f32_32x32x16_bf16 v[2:17], v[66:69], v[74:77], v[2:17]
	v_mfma_f32_32x32x16_bf16 v[50:65], v[66:69], v[78:81], v[50:65]
	v_mfma_f32_32x32x16_bf16 v[34:49], v[70:73], v[74:77], v[34:49]
	v_mfma_f32_32x32x16_bf16 v[18:33], v[70:73], v[78:81], v[18:33]
	ds_read_b128 v[66:69], v223 offset:34816
	ds_read_b128 v[70:73], v223 offset:38912
	ds_read_b128 v[74:77], v227 offset:34816
	ds_read_b128 v[78:81], v227 offset:38912
	v_mfma_f32_32x32x16_bf16 v[2:17], v[82:85], v[90:93], v[2:17]
	v_mfma_f32_32x32x16_bf16 v[50:65], v[82:85], v[94:97], v[50:65]
	v_mfma_f32_32x32x16_bf16 v[34:49], v[86:89], v[90:93], v[34:49]
	v_mfma_f32_32x32x16_bf16 v[18:33], v[86:89], v[94:97], v[18:33]
	ds_read_b128 v[82:85], v224 offset:34816
	ds_read_b128 v[86:89], v224 offset:38912
	ds_read_b128 v[90:93], v228 offset:34816
	ds_read_b128 v[94:97], v228 offset:38912
	s_waitcnt lgkmcnt(8)
	v_mfma_f32_32x32x16_bf16 v[2:17], v[230:233], v[238:241], v[2:17]
	v_mfma_f32_32x32x16_bf16 v[50:65], v[230:233], v[242:245], v[50:65]
	v_mfma_f32_32x32x16_bf16 v[34:49], v[234:237], v[238:241], v[34:49]
	v_mfma_f32_32x32x16_bf16 v[18:33], v[234:237], v[242:245], v[18:33]
	ds_read_b128 v[230:233], v225 offset:34816
	ds_read_b128 v[234:237], v225 offset:38912
	ds_read_b128 v[238:241], v229 offset:34816
	ds_read_b128 v[242:245], v229 offset:38912
	s_waitcnt lgkmcnt(8)
	v_mfma_f32_32x32x16_bf16 v[2:17], v[66:69], v[74:77], v[2:17]
	v_mfma_f32_32x32x16_bf16 v[50:65], v[66:69], v[78:81], v[50:65]
	v_mfma_f32_32x32x16_bf16 v[34:49], v[70:73], v[74:77], v[34:49]
	v_mfma_f32_32x32x16_bf16 v[18:33], v[70:73], v[78:81], v[18:33]
	s_waitcnt lgkmcnt(0)
	s_barrier
	s_add_u32 m0, s14, 0x8480
	s_nop 0
	global_load_lds_dwordx4 v[102:103], off offset:896
	s_add_u32 m0, s14, 0x9480
	s_nop 0
	global_load_lds_dwordx4 v[104:105], off offset:896
	s_add_u32 m0, s14, 0xa480
	s_nop 0
	global_load_lds_dwordx4 v[108:109], off offset:896
	s_add_u32 m0, s14, 0xb480
	s_nop 0
	global_load_lds_dwordx4 v[112:113], off offset:896
	s_add_u32 m0, s14, 0xc480
	s_nop 0
	global_load_lds_dwordx4 v[100:101], off offset:896
	s_add_u32 m0, s14, 0xd480
	s_nop 0
	global_load_lds_dwordx4 v[106:107], off offset:896
	s_add_u32 m0, s14, 0xe480
	s_nop 0
	global_load_lds_dwordx4 v[110:111], off offset:896
	s_add_u32 m0, s14, 0xf480
	s_nop 0
	global_load_lds_dwordx4 v[114:115], off offset:896
	s_waitcnt vmcnt(8)
	s_barrier
	ds_read_b128 v[66:69], v222 offset:2048
	ds_read_b128 v[70:73], v222 offset:6144
	ds_read_b128 v[74:77], v226 offset:2048
	ds_read_b128 v[78:81], v226 offset:6144
	v_mfma_f32_32x32x16_bf16 v[2:17], v[82:85], v[90:93], v[2:17]
	v_mfma_f32_32x32x16_bf16 v[50:65], v[82:85], v[94:97], v[50:65]
	v_mfma_f32_32x32x16_bf16 v[34:49], v[86:89], v[90:93], v[34:49]
	v_mfma_f32_32x32x16_bf16 v[18:33], v[86:89], v[94:97], v[18:33]
	ds_read_b128 v[82:85], v223 offset:2048
	ds_read_b128 v[86:89], v223 offset:6144
	ds_read_b128 v[90:93], v227 offset:2048
	ds_read_b128 v[94:97], v227 offset:6144
	v_mfma_f32_32x32x16_bf16 v[2:17], v[230:233], v[238:241], v[2:17]
	v_mfma_f32_32x32x16_bf16 v[50:65], v[230:233], v[242:245], v[50:65]
	v_mfma_f32_32x32x16_bf16 v[34:49], v[234:237], v[238:241], v[34:49]
	v_mfma_f32_32x32x16_bf16 v[18:33], v[234:237], v[242:245], v[18:33]
	ds_read_b128 v[230:233], v224 offset:2048
	ds_read_b128 v[234:237], v224 offset:6144
	ds_read_b128 v[238:241], v228 offset:2048
	ds_read_b128 v[242:245], v228 offset:6144
	s_waitcnt lgkmcnt(8)
	v_mfma_f32_32x32x16_bf16 v[2:17], v[66:69], v[74:77], v[2:17]
	v_mfma_f32_32x32x16_bf16 v[50:65], v[66:69], v[78:81], v[50:65]
	v_mfma_f32_32x32x16_bf16 v[34:49], v[70:73], v[74:77], v[34:49]
	v_mfma_f32_32x32x16_bf16 v[18:33], v[70:73], v[78:81], v[18:33]
	ds_read_b128 v[66:69], v225 offset:2048
	ds_read_b128 v[70:73], v225 offset:6144
	ds_read_b128 v[74:77], v229 offset:2048
	ds_read_b128 v[78:81], v229 offset:6144
	s_waitcnt lgkmcnt(8)
	v_mfma_f32_32x32x16_bf16 v[2:17], v[82:85], v[90:93], v[2:17]
	v_mfma_f32_32x32x16_bf16 v[50:65], v[82:85], v[94:97], v[50:65]
	v_mfma_f32_32x32x16_bf16 v[34:49], v[86:89], v[90:93], v[34:49]
	v_mfma_f32_32x32x16_bf16 v[18:33], v[86:89], v[94:97], v[18:33]
	s_waitcnt lgkmcnt(0)
	s_waitcnt vmcnt(0)
	s_barrier
	ds_read_b128 v[82:85], v222 offset:34816
	ds_read_b128 v[86:89], v222 offset:38912
	ds_read_b128 v[90:93], v226 offset:34816
	ds_read_b128 v[94:97], v226 offset:38912
	v_mfma_f32_32x32x16_bf16 v[2:17], v[230:233], v[238:241], v[2:17]
	v_mfma_f32_32x32x16_bf16 v[50:65], v[230:233], v[242:245], v[50:65]
	v_mfma_f32_32x32x16_bf16 v[34:49], v[234:237], v[238:241], v[34:49]
	v_mfma_f32_32x32x16_bf16 v[18:33], v[234:237], v[242:245], v[18:33]
	ds_read_b128 v[230:233], v223 offset:34816
	ds_read_b128 v[234:237], v223 offset:38912
	ds_read_b128 v[238:241], v227 offset:34816
	ds_read_b128 v[242:245], v227 offset:38912
	v_mfma_f32_32x32x16_bf16 v[2:17], v[66:69], v[74:77], v[2:17]
	v_mfma_f32_32x32x16_bf16 v[50:65], v[66:69], v[78:81], v[50:65]
	v_mfma_f32_32x32x16_bf16 v[34:49], v[70:73], v[74:77], v[34:49]
	v_mfma_f32_32x32x16_bf16 v[18:33], v[70:73], v[78:81], v[18:33]
	ds_read_b128 v[66:69], v224 offset:34816
	ds_read_b128 v[70:73], v224 offset:38912
	ds_read_b128 v[74:77], v228 offset:34816
	ds_read_b128 v[78:81], v228 offset:38912
	s_waitcnt lgkmcnt(8)
	v_mfma_f32_32x32x16_bf16 v[2:17], v[82:85], v[90:93], v[2:17]
	v_mfma_f32_32x32x16_bf16 v[50:65], v[82:85], v[94:97], v[50:65]
	v_mfma_f32_32x32x16_bf16 v[34:49], v[86:89], v[90:93], v[34:49]
	v_mfma_f32_32x32x16_bf16 v[18:33], v[86:89], v[94:97], v[18:33]
	ds_read_b128 v[82:85], v225 offset:34816
	ds_read_b128 v[86:89], v225 offset:38912
	ds_read_b128 v[90:93], v229 offset:34816
	ds_read_b128 v[94:97], v229 offset:38912
	s_waitcnt lgkmcnt(8)
	v_mfma_f32_32x32x16_bf16 v[2:17], v[230:233], v[238:241], v[2:17]
	v_mfma_f32_32x32x16_bf16 v[50:65], v[230:233], v[242:245], v[50:65]
	v_mfma_f32_32x32x16_bf16 v[34:49], v[234:237], v[238:241], v[34:49]
	v_mfma_f32_32x32x16_bf16 v[18:33], v[234:237], v[242:245], v[18:33]
	s_waitcnt lgkmcnt(0)
	v_mfma_f32_32x32x16_bf16 v[2:17], v[66:69], v[74:77], v[2:17]
	v_mfma_f32_32x32x16_bf16 v[50:65], v[66:69], v[78:81], v[50:65]
	v_mfma_f32_32x32x16_bf16 v[34:49], v[70:73], v[74:77], v[34:49]
	v_mfma_f32_32x32x16_bf16 v[18:33], v[70:73], v[78:81], v[18:33]
	v_mfma_f32_32x32x16_bf16 v[2:17], v[82:85], v[90:93], v[2:17]
	v_mfma_f32_32x32x16_bf16 v[50:65], v[82:85], v[94:97], v[50:65]
	v_mfma_f32_32x32x16_bf16 v[34:49], v[86:89], v[90:93], v[34:49]
	v_mfma_f32_32x32x16_bf16 v[18:33], v[86:89], v[94:97], v[18:33]
	s_nop 7
	s_nop 7
	s_mov_b64 s[0:1], -1
	s_cmp_eq_u32 s45, 2
	v_and_b32_e32 v92, 0xffff0000, v169
	v_lshlrev_b32_e32 v96, 16, v206
	v_and_b32_e32 v99, 0xffff0000, v206
	v_lshlrev_b32_e32 v100, 16, v207
	v_and_b32_e32 v108, 0xffff0000, v209
	v_lshlrev_b32_e32 v110, 16, v210
	v_and_b32_e32 v111, 0xffff0000, v210
	v_and_b32_e32 v104, 0xffff0000, v207
	v_lshlrev_b32_e32 v105, 16, v208
	v_and_b32_e32 v106, 0xffff0000, v208
	v_lshlrev_b32_e32 v107, 16, v209
	v_lshlrev_b32_e32 v112, 16, v211
	v_and_b32_e32 v114, 0xffff0000, v211
	v_and_b32_e32 v82, 0xffff0000, v171
	v_lshlrev_b32_e32 v83, 16, v170
	v_and_b32_e32 v86, 0xffff0000, v170
	v_lshlrev_b32_e32 v89, 16, v169
	v_cvt_f32_ubyte0_e32 v0, v116
	v_mul_f32_e32 v0, 0x3b808081, v0
	v_lshlrev_b32_e32 v116, 16, v212
	s_waitcnt lgkmcnt(0)
	s_barrier
	s_nop 0
	s_nop 0
	v_cvt_f32_ubyte2_e32 v67, v117
	v_mul_f32_e32 v67, 0x3b808081, v67
	s_nop 8
	v_mul_f32_e32 v4, v67, v4
	v_cvt_f32_ubyte3_e32 v67, v117
	v_mul_f32_e32 v67, 0x3b808081, v67
	v_mul_f32_e32 v5, v67, v5
	v_cvt_f32_ubyte0_e32 v67, v119
	v_mul_f32_e32 v67, 0x3b808081, v67
	v_mul_f32_e32 v6, v67, v6
	v_cvt_f32_ubyte1_e32 v67, v121
	v_mul_f32_e32 v67, 0x3b808081, v67
	v_mul_f32_e32 v7, v67, v7
	v_cvt_f32_ubyte2_e32 v67, v120
	v_mul_f32_e32 v67, 0x3b808081, v67
	v_mul_f32_e32 v8, v67, v8
	v_cvt_f32_ubyte3_e32 v67, v120
	v_mul_f32_e32 v67, 0x3b808081, v67
	v_mul_f32_e32 v9, v67, v9
	v_cvt_f32_ubyte0_e32 v67, v122
	v_mul_f32_e32 v67, 0x3b808081, v67
	v_mul_f32_e32 v10, v67, v10
	v_cvt_f32_ubyte1_e32 v67, v124
	v_mul_f32_e32 v67, 0x3b808081, v67
	v_mul_f32_e32 v11, v67, v11
	v_cvt_f32_ubyte2_e32 v67, v123
	v_mul_f32_e32 v67, 0x3b808081, v67
	v_mul_f32_e32 v12, v67, v12
	v_cvt_f32_ubyte3_e32 v67, v123
	v_mul_f32_e32 v67, 0x3b808081, v67
	v_mul_f32_e32 v13, v67, v13
	v_cvt_f32_ubyte0_e32 v67, v125
	v_mul_f32_e32 v67, 0x3b808081, v67
	v_mul_f32_e32 v14, v67, v14
	v_cvt_f32_ubyte1_e32 v67, v127
	v_mul_f32_e32 v67, 0x3b808081, v67
	v_mul_f32_e32 v15, v67, v15
	v_cvt_f32_ubyte2_e32 v67, v126
	v_mul_f32_e32 v67, 0x3b808081, v67
	v_mul_f32_e32 v67, v67, v16
	v_cvt_f32_ubyte3_e32 v16, v126
	v_mul_f32_e32 v16, 0x3b808081, v16
	v_mul_f32_e32 v68, v16, v17
	v_cvt_f32_ubyte0_e32 v16, v128
	v_mul_f32_e32 v16, 0x3b808081, v16
	v_mul_f32_e32 v50, v16, v50
	v_cvt_f32_ubyte1_e32 v16, v130
	v_mul_f32_e32 v16, 0x3b808081, v16
	v_mul_f32_e32 v51, v16, v51
	v_cvt_f32_ubyte2_e32 v16, v129
	v_mul_f32_e32 v16, 0x3b808081, v16
	v_mul_f32_e32 v52, v16, v52
	v_cvt_f32_ubyte3_e32 v16, v129
	v_mul_f32_e32 v16, 0x3b808081, v16
	v_mul_f32_e32 v53, v16, v53
	v_cvt_f32_ubyte0_e32 v16, v131
	v_mul_f32_e32 v16, 0x3b808081, v16
	v_mul_f32_e32 v54, v16, v54
	v_cvt_f32_ubyte1_e32 v16, v133
	v_mul_f32_e32 v16, 0x3b808081, v16
	v_mul_f32_e32 v55, v16, v55
	v_cvt_f32_ubyte2_e32 v16, v132
	v_mul_f32_e32 v16, 0x3b808081, v16
	v_mul_f32_e32 v56, v16, v56
	v_cvt_f32_ubyte3_e32 v16, v132
	v_mul_f32_e32 v16, 0x3b808081, v16
	v_mul_f32_e32 v57, v16, v57
	v_cvt_f32_ubyte0_e32 v16, v134
	v_mul_f32_e32 v16, 0x3b808081, v16
	v_mul_f32_e32 v58, v16, v58
	v_cvt_f32_ubyte1_e32 v16, v136
	v_mul_f32_e32 v16, 0x3b808081, v16
	v_mul_f32_e32 v59, v16, v59
	v_cvt_f32_ubyte2_e32 v16, v135
	v_mul_f32_e32 v16, 0x3b808081, v16
	v_mul_f32_e32 v60, v16, v60
	v_cvt_f32_ubyte3_e32 v16, v135
	v_mul_f32_e32 v16, 0x3b808081, v16
	v_mul_f32_e32 v61, v16, v61
	v_cvt_f32_ubyte0_e32 v16, v137
	v_mul_f32_e32 v16, 0x3b808081, v16
	s_nop 0
	v_mul_f32_e32 v62, v16, v62
	v_cvt_f32_ubyte1_e32 v16, v139
	v_mul_f32_e32 v16, 0x3b808081, v16
	v_mul_f32_e32 v63, v16, v63
	v_cvt_f32_ubyte2_e32 v16, v138
	v_mul_f32_e32 v16, 0x3b808081, v16
	v_mul_f32_e32 v64, v16, v64
	v_cvt_f32_ubyte3_e32 v16, v138
	v_mul_f32_e32 v16, 0x3b808081, v16
	v_mul_f32_e32 v65, v16, v65
	v_cvt_f32_ubyte0_e32 v16, v140
	v_mul_f32_e32 v16, 0x3b808081, v16
	v_mul_f32_e32 v34, v16, v34
	v_cvt_f32_ubyte1_e32 v16, v142
	v_mul_f32_e32 v16, 0x3b808081, v16
	v_mul_f32_e32 v35, v16, v35
	v_cvt_f32_ubyte2_e32 v16, v141
	v_mul_f32_e32 v16, 0x3b808081, v16
	v_mul_f32_e32 v36, v16, v36
	v_cvt_f32_ubyte3_e32 v16, v141
	v_mul_f32_e32 v16, 0x3b808081, v16
	v_mul_f32_e32 v37, v16, v37
	v_cvt_f32_ubyte0_e32 v16, v143
	v_mul_f32_e32 v16, 0x3b808081, v16
	v_mul_f32_e32 v38, v16, v38
	v_cvt_f32_ubyte1_e32 v16, v145
	v_mul_f32_e32 v16, 0x3b808081, v16
	v_mul_f32_e32 v39, v16, v39
	v_cvt_f32_ubyte2_e32 v16, v144
	v_mul_f32_e32 v16, 0x3b808081, v16
	v_mul_f32_e32 v40, v16, v40
	v_cvt_f32_ubyte3_e32 v16, v144
	v_mul_f32_e32 v16, 0x3b808081, v16
	v_mul_f32_e32 v69, v16, v41
	v_cvt_f32_ubyte0_e32 v16, v146
	v_mul_f32_e32 v16, 0x3b808081, v16
	s_nop 0
	v_mul_f32_e32 v70, v16, v42
	v_cvt_f32_ubyte1_e32 v16, v148
	v_mul_f32_e32 v16, 0x3b808081, v16
	v_mul_f32_e32 v76, v16, v43
	v_cvt_f32_ubyte2_e32 v16, v147
	v_mul_f32_e32 v16, 0x3b808081, v16
	v_mul_f32_e32 v78, v16, v44
	v_cvt_f32_ubyte3_e32 v16, v147
	v_mul_f32_e32 v16, 0x3b808081, v16
	v_mul_f32_e32 v81, v16, v45
	v_cvt_f32_ubyte0_e32 v16, v149
	v_mul_f32_e32 v16, 0x3b808081, v16
	v_mul_f32_e32 v93, v16, v46
	v_cvt_f32_ubyte1_e32 v16, v151
	v_mul_f32_e32 v16, 0x3b808081, v16
	v_mul_f32_e32 v101, v16, v47
	v_cvt_f32_ubyte2_e32 v16, v150
	v_mul_f32_e32 v16, 0x3b808081, v16
	v_mul_f32_e32 v109, v16, v48
	v_cvt_f32_ubyte3_e32 v16, v150
	v_mul_f32_e32 v16, 0x3b808081, v16
	v_mul_f32_e32 v113, v16, v49
	v_cvt_f32_ubyte0_e32 v16, v152
	v_mul_f32_e32 v16, 0x3b808081, v16
	v_mul_f32_e32 v115, v16, v18
	v_cvt_f32_ubyte1_e32 v16, v154
	v_mul_f32_e32 v16, 0x3b808081, v16
	v_mul_f32_e32 v117, v16, v19
	v_cvt_f32_ubyte2_e32 v16, v153
	v_mul_f32_e32 v16, 0x3b808081, v16
	v_cvt_f32_ubyte1_e32 v66, v118
	v_mul_f32_e32 v118, v16, v20
	v_cvt_f32_ubyte3_e32 v16, v153
	v_mul_f32_e32 v16, 0x3b808081, v16
	v_mul_f32_e32 v119, v16, v21
	v_cvt_f32_ubyte0_e32 v16, v155
	v_mul_f32_e32 v16, 0x3b808081, v16
	v_mul_f32_e32 v120, v16, v22
	v_cvt_f32_ubyte1_e32 v16, v157
	v_mul_f32_e32 v16, 0x3b808081, v16
	v_mul_f32_e32 v122, v16, v23
	v_cvt_f32_ubyte2_e32 v16, v156
	v_mul_f32_e32 v16, 0x3b808081, v16
	v_mul_f32_e32 v123, v16, v24
	v_cvt_f32_ubyte3_e32 v16, v156
	v_mul_f32_e32 v16, 0x3b808081, v16
	v_mul_f32_e32 v124, v16, v25
	v_cvt_f32_ubyte0_e32 v16, v158
	v_mul_f32_e32 v16, 0x3b808081, v16
	v_mul_f32_e32 v125, v16, v26
	v_cvt_f32_ubyte1_e32 v16, v160
	v_mul_f32_e32 v16, 0x3b808081, v16
	v_mul_f32_e32 v127, v16, v27
	v_cvt_f32_ubyte2_e32 v16, v159
	v_mul_f32_e32 v16, 0x3b808081, v16
	v_mul_f32_e32 v128, v16, v28
	v_cvt_f32_ubyte3_e32 v16, v159
	v_mul_f32_e32 v16, 0x3b808081, v16
	v_mul_f32_e32 v129, v16, v29
	v_cvt_f32_ubyte0_e32 v16, v161
	v_mul_f32_e32 v16, 0x3b808081, v16
	v_mul_f32_e32 v130, v16, v30
	v_cvt_f32_ubyte1_e32 v16, v163
	v_mul_f32_e32 v16, 0x3b808081, v16
	v_mul_f32_e32 v132, v16, v31
	v_cvt_f32_ubyte2_e32 v16, v162
	v_mul_f32_e32 v16, 0x3b808081, v16
	v_mul_f32_e32 v133, v16, v32
	v_cvt_f32_ubyte3_e32 v16, v162
	v_mul_f32_e32 v16, 0x3b808081, v16
	v_mul_f32_e32 v66, 0x3b808081, v66
	v_mul_f32_e32 v134, v16, v33
	v_lshlrev_b32_e32 v16, 16, v205
	v_and_b32_e32 v17, 0xffff0000, v205
	v_lshlrev_b32_e32 v18, 16, v204
	v_and_b32_e32 v19, 0xffff0000, v204
	v_lshlrev_b32_e32 v20, 16, v203
	v_and_b32_e32 v21, 0xffff0000, v203
	v_lshlrev_b32_e32 v22, 16, v202
	v_and_b32_e32 v23, 0xffff0000, v202
	v_lshlrev_b32_e32 v24, 16, v201
	v_and_b32_e32 v25, 0xffff0000, v201
	v_lshlrev_b32_e32 v28, 16, v200
	v_and_b32_e32 v31, 0xffff0000, v200
	v_lshlrev_b32_e32 v41, 16, v199
	v_and_b32_e32 v44, 0xffff0000, v199
	v_lshlrev_b32_e32 v45, 16, v177
	v_and_b32_e32 v46, 0xffff0000, v177
	v_lshlrev_b32_e32 v47, 16, v176
	v_and_b32_e32 v48, 0xffff0000, v176
	v_lshlrev_b32_e32 v49, 16, v175
	v_and_b32_e32 v71, 0xffff0000, v175
	v_lshlrev_b32_e32 v72, 16, v174
	v_and_b32_e32 v73, 0xffff0000, v174
	v_lshlrev_b32_e32 v74, 16, v173
	v_and_b32_e32 v75, 0xffff0000, v173
	v_lshlrev_b32_e32 v77, 16, v172
	v_and_b32_e32 v79, 0xffff0000, v172
	v_lshlrev_b32_e32 v80, 16, v171
	v_and_b32_e32 v121, 0xffff0000, v212
	v_lshlrev_b32_e32 v126, 16, v213
	v_and_b32_e32 v131, 0xffff0000, v213
	v_lshlrev_b32_e32 v135, 16, v214
	v_and_b32_e32 v136, 0xffff0000, v214
	v_lshlrev_b32_e32 v137, 16, v215
	v_and_b32_e32 v138, 0xffff0000, v215
	v_lshlrev_b32_e32 v139, 16, v216
	v_and_b32_e32 v140, 0xffff0000, v216
	v_lshlrev_b32_e32 v141, 16, v217
	v_and_b32_e32 v142, 0xffff0000, v217
	v_lshlrev_b32_e32 v143, 16, v218
	v_and_b32_e32 v144, 0xffff0000, v218
	v_lshlrev_b32_e32 v145, 16, v219
	v_and_b32_e32 v146, 0xffff0000, v219
	v_lshlrev_b32_e32 v147, 16, v220
	v_and_b32_e32 v148, 0xffff0000, v220
	v_lshlrev_b32_e32 v149, 16, v221
	v_and_b32_e32 v150, 0xffff0000, v221
	v_fmac_f32_e32 v16, v0, v2
	v_fmac_f32_e32 v17, v66, v3
	v_add_f32_e32 v42, v4, v18
	v_add_f32_e32 v43, v5, v19
	v_add_f32_e32 v32, v6, v20
	v_add_f32_e32 v33, v7, v21
	v_add_f32_e32 v29, v8, v22
	v_add_f32_e32 v30, v9, v23
	v_add_f32_e32 v26, v10, v24
	v_add_f32_e32 v27, v11, v25
	v_add_f32_e32 v23, v12, v28
	v_add_f32_e32 v24, v13, v31
	v_add_f32_e32 v21, v14, v41
	v_add_f32_e32 v20, v15, v44
	v_add_f32_e32 v19, v67, v45
	v_add_f32_e32 v18, v68, v46
	v_add_f32_e32 v102, v50, v47
	v_add_f32_e32 v103, v51, v48
	v_add_f32_e32 v97, v52, v49
	v_add_f32_e32 v98, v53, v71
	v_add_f32_e32 v94, v54, v72
	v_add_f32_e32 v95, v55, v73
	v_add_f32_e32 v90, v56, v74
	v_add_f32_e32 v91, v57, v75
	v_add_f32_e32 v87, v58, v77
	v_add_f32_e32 v88, v59, v79
	v_add_f32_e32 v84, v60, v80
	v_add_f32_e32 v85, v61, v82
	v_add_f32_e32 v82, v62, v83
	v_add_f32_e32 v80, v63, v86
	v_add_f32_e32 v79, v64, v89
	v_add_f32_e32 v77, v65, v92
	v_add_f32_e32 v75, v34, v96
	v_add_f32_e32 v73, v35, v99
	v_add_f32_e32 v74, v36, v100
	v_add_f32_e32 v72, v37, v104
	v_add_f32_e32 v71, v38, v105
	v_add_f32_e32 v48, v39, v106
	v_add_f32_e32 v49, v40, v107
	v_add_f32_e32 v47, v69, v108
	v_add_f32_e32 v46, v70, v110
	v_add_f32_e32 v44, v76, v111
	v_add_f32_e32 v45, v78, v112
	v_add_f32_e32 v41, v81, v114
	v_add_f32_e32 v31, v93, v116
	v_add_f32_e32 v28, v101, v121
	v_add_f32_e32 v25, v109, v126
	v_add_f32_e32 v22, v113, v131
	v_add_f32_e32 v114, v115, v135
	v_add_f32_e32 v111, v117, v136
	v_add_f32_e32 v112, v118, v137
	v_add_f32_e32 v110, v119, v138
	v_add_f32_e32 v108, v120, v139
	v_add_f32_e32 v106, v122, v140
	v_add_f32_e32 v107, v123, v141
	v_add_f32_e32 v105, v124, v142
	v_add_f32_e32 v104, v125, v143
	v_add_f32_e32 v99, v127, v144
	v_add_f32_e32 v100, v128, v145
	v_add_f32_e32 v96, v129, v146
	v_add_f32_e32 v92, v130, v147
	v_add_f32_e32 v89, v132, v148
	v_add_f32_e32 v86, v133, v149
	v_add_f32_e32 v83, v134, v150
	s_cbranch_scc1 .LBB0_857
	v_mul_f32_e32 v0, v0, v2
	v_mul_f32_e32 v2, v66, v3
	v_cndmask_b32_e32 v0, v16, v0, vcc
	v_cndmask_b32_e32 v2, v17, v2, vcc
	v_cvt_pk_bf16_f32 v116, v0, v2
	v_cndmask_b32_e32 v0, v42, v4, vcc
	v_cndmask_b32_e32 v2, v43, v5, vcc
	v_cvt_pk_bf16_f32 v121, v0, v2
	v_cndmask_b32_e32 v0, v32, v6, vcc
	v_cndmask_b32_e32 v2, v33, v7, vcc
	v_cvt_pk_bf16_f32 v126, v0, v2
	v_cndmask_b32_e32 v0, v29, v8, vcc
	v_cndmask_b32_e32 v2, v30, v9, vcc
	v_cvt_pk_bf16_f32 v131, v0, v2
	v_cndmask_b32_e32 v0, v26, v10, vcc
	v_cndmask_b32_e32 v2, v27, v11, vcc
	v_cvt_pk_bf16_f32 v135, v0, v2
	v_cndmask_b32_e32 v0, v23, v12, vcc
	v_cndmask_b32_e32 v2, v24, v13, vcc
	v_cvt_pk_bf16_f32 v136, v0, v2
	v_cndmask_b32_e32 v0, v21, v14, vcc
	v_cndmask_b32_e32 v2, v20, v15, vcc
	v_cvt_pk_bf16_f32 v137, v0, v2
	v_cndmask_b32_e32 v0, v19, v67, vcc
	v_cndmask_b32_e32 v2, v18, v68, vcc
	v_cvt_pk_bf16_f32 v138, v0, v2
	v_cndmask_b32_e32 v0, v102, v50, vcc
	v_cndmask_b32_e32 v2, v103, v51, vcc
	v_cvt_pk_bf16_f32 v155, v0, v2
	v_cndmask_b32_e32 v0, v97, v52, vcc
	v_cndmask_b32_e32 v2, v98, v53, vcc
	v_cvt_pk_bf16_f32 v156, v0, v2
	v_cndmask_b32_e32 v0, v94, v54, vcc
	v_cndmask_b32_e32 v2, v95, v55, vcc
	v_cvt_pk_bf16_f32 v157, v0, v2
	v_cndmask_b32_e32 v0, v90, v56, vcc
	v_cndmask_b32_e32 v2, v91, v57, vcc
	v_cvt_pk_bf16_f32 v158, v0, v2
	v_cndmask_b32_e32 v0, v87, v58, vcc
	v_cndmask_b32_e32 v2, v88, v59, vcc
	v_cvt_pk_bf16_f32 v159, v0, v2
	v_cndmask_b32_e32 v0, v84, v60, vcc
	v_cndmask_b32_e32 v2, v85, v61, vcc
	v_cvt_pk_bf16_f32 v160, v0, v2
	v_cndmask_b32_e32 v0, v82, v62, vcc
	v_cndmask_b32_e32 v2, v80, v63, vcc
	v_cvt_pk_bf16_f32 v161, v0, v2
	v_cndmask_b32_e32 v0, v79, v64, vcc
	v_cndmask_b32_e32 v2, v77, v65, vcc
	v_cvt_pk_bf16_f32 v162, v0, v2
	v_cndmask_b32_e32 v0, v75, v34, vcc
	v_cndmask_b32_e32 v2, v73, v35, vcc
	v_cvt_pk_bf16_f32 v154, v0, v2
	v_cndmask_b32_e32 v0, v74, v36, vcc
	v_cndmask_b32_e32 v2, v72, v37, vcc
	v_cvt_pk_bf16_f32 v153, v0, v2
	v_cndmask_b32_e32 v0, v71, v38, vcc
	v_cndmask_b32_e32 v2, v48, v39, vcc
	v_cvt_pk_bf16_f32 v152, v0, v2
	v_cndmask_b32_e32 v0, v49, v40, vcc
	v_cndmask_b32_e32 v2, v47, v69, vcc
	v_cvt_pk_bf16_f32 v151, v0, v2
	v_cndmask_b32_e32 v0, v46, v70, vcc
	v_cndmask_b32_e32 v2, v44, v76, vcc
	v_cvt_pk_bf16_f32 v150, v0, v2
	v_cndmask_b32_e32 v0, v45, v78, vcc
	v_cndmask_b32_e32 v2, v41, v81, vcc
	v_cvt_pk_bf16_f32 v149, v0, v2
	v_cndmask_b32_e32 v0, v31, v93, vcc
	v_cndmask_b32_e32 v2, v28, v101, vcc
	v_cvt_pk_bf16_f32 v148, v0, v2
	v_cndmask_b32_e32 v0, v25, v109, vcc
	v_cndmask_b32_e32 v2, v22, v113, vcc
	v_cvt_pk_bf16_f32 v147, v0, v2
	v_cndmask_b32_e32 v0, v114, v115, vcc
	v_cndmask_b32_e32 v2, v111, v117, vcc
	v_cvt_pk_bf16_f32 v146, v0, v2
	v_cndmask_b32_e32 v0, v112, v118, vcc
	v_cndmask_b32_e32 v2, v110, v119, vcc
	v_cvt_pk_bf16_f32 v145, v0, v2
	v_cndmask_b32_e32 v0, v108, v120, vcc
	v_cndmask_b32_e32 v2, v106, v122, vcc
	v_cvt_pk_bf16_f32 v144, v0, v2
	v_cndmask_b32_e32 v0, v107, v123, vcc
	v_cndmask_b32_e32 v2, v105, v124, vcc
	v_cvt_pk_bf16_f32 v143, v0, v2
	v_cndmask_b32_e32 v0, v104, v125, vcc
	v_cndmask_b32_e32 v2, v99, v127, vcc
	v_cvt_pk_bf16_f32 v142, v0, v2
	v_cndmask_b32_e32 v0, v100, v128, vcc
	v_cndmask_b32_e32 v2, v96, v129, vcc
	v_cvt_pk_bf16_f32 v141, v0, v2
	v_cndmask_b32_e32 v0, v92, v130, vcc
	v_cndmask_b32_e32 v2, v89, v132, vcc
	v_cvt_pk_bf16_f32 v140, v0, v2
	v_cndmask_b32_e32 v0, v86, v133, vcc
	v_cndmask_b32_e32 v2, v83, v134, vcc
	v_cvt_pk_bf16_f32 v139, v0, v2
	s_mov_b64 s[0:1], 0
